# GEMM store epilogues (in-proj, up-proj): LDS parking area moved off the last K-tile's stage, its two workgroup barriers removed
# speedup vs baseline: 1.0101x; 1.0101x over previous
; #define TID (opq_v((int)threadIdx.x))
; template <int NI>
; DEVINL void gemm_kloop(const bf16_t* __restrict__ A, int lda, const bf16_t* __restrict__ Bt, int ldb, int K, int m0, int n0,
;                        unsigned char* lds, f32x16 (&acc)[NI][2]) {
;     const int tid = TID, lane = tid & 63, w = tid >> 6, wm = w & 3, wn = w >> 2, r = lane & 31, h = lane >> 5;
;     const int lrow = tid >> 3, cg = (tid & 7) ^ ((tid >> 4) & 7);
;     const bf16_t* ga = A + (size_t)(m0 + lrow) * lda + cg * 8;
;     const bf16_t* gb = Bt + (size_t)(n0 + lrow) * ldb + cg * 8;
;     unsigned char* da = lds + tid * 16;
;     unsigned char* db = lds + A_ST + tid * 16;
;     ...
;     const int nt = K >> 6;
;     asm volatile("s_waitcnt lgkmcnt(0)" ::: "memory");
;     __builtin_amdgcn_s_barrier();
;     GEMM_ISSUE(0, 0);
;     if (nt > 1) GEMM_ISSUE(1, 1);
;     const int sw = (r >> 1) & 7;
;     int o4[4];
; #pragma unroll
;     for (int ks = 0; ks < 4; ++ks) o4[ks] = ((ks * 2 + h) ^ sw) * 16;
;     int cur = 0;
;     auto compute = [&](int st_) {
;         const unsigned char* pa = lds + st_ * STAGE + (wm * 64 + r) * 128;
;         const unsigned char* pb = lds + st_ * STAGE + A_ST + (wn * 32 * NI + r) * 128;
;         bf16x8 af[2][2], bfr[2][NI];
; #pragma unroll
;         for (int i = 0; i < 2; ++i) af[0][i] = *(const bf16x8*)(pa + i * 32 * 128 + o4[0]);
; #pragma unroll
;         for (int i = 0; i < NI; ++i) bfr[0][i] = *(const bf16x8*)(pb + i * 32 * 128 + o4[0]);
; #pragma unroll
;         for (int ks = 0; ks < 4; ++ks) {
;             if (ks < 3) {
; #pragma unroll
;                 for (int i = 0; i < 2; ++i) af[(ks + 1) & 1][i] = *(const bf16x8*)(pa + i * 32 * 128 + o4[ks + 1]);
; #pragma unroll
;                 for (int i = 0; i < NI; ++i) bfr[(ks + 1) & 1][i] = *(const bf16x8*)(pb + i * 32 * 128 + o4[ks + 1]);
;             }
; #pragma unroll
;             for (int ni = 0; ni < NI; ++ni)
; #pragma unroll
;                 for (int mi = 0; mi < 2; ++mi) acc[ni][mi] = MFMA32(bfr[ks & 1][ni], af[ks & 1][mi], acc[ni][mi]);
;         }
;     };
;     int t = 0;
;     for (; t + 2 < nt; ++t) {
;         if (NI == 2) asm volatile("s_waitcnt vmcnt(6)" ::: "memory"); else asm volatile("s_waitcnt vmcnt(5)" ::: "memory");
;         __builtin_amdgcn_s_barrier();
;         { const int s2 = (cur >= 1) ? cur - 1 : 2; GEMM_ISSUE(s2, t + 2); }
;         compute(cur);
.LBB0_45:
	s_mul_hi_i32 s1, s0, 0x78787879
	s_lshr_b32 s4, s1, 31
	s_ashr_i32 s1, s1, 8
	s_add_i32 s1, s1, s4
	s_mul_i32 s4, s1, 0xfffffde0
	s_add_i32 s4, s0, s4
	s_ashr_i32 s5, s4, 31
	s_lshr_b32 s5, s5, 29
	s_add_i32 s5, s4, s5
	s_and_b32 s6, s5, 0x1fffff8
	s_sub_i32 s6, s4, s6
	s_lshl_b32 s4, s5, 5
	v_mov_b32_e32 v4, v160
	s_and_b32 s4, s4, 0xffffff00
	s_lshl_b32 s1, s1, 10
	v_ashrrev_i32_e32 v2, 3, v4
	v_lshrrev_b32_e32 v0, 4, v4
	v_xor_b32_e32 v3, v0, v4
	v_add_u32_e32 v0, s4, v2
	v_ashrrev_i32_e32 v1, 31, v0
	s_lshl_b32 s5, s6, 7
	v_lshlrev_b64 v[0:1], 11, v[0:1]
	v_lshlrev_b32_e32 v3, 4, v3
	v_lshl_add_u32 v89, v4, 4, 0
	s_add_i32 s1, s5, s1
	v_lshl_add_u64 v[0:1], s[22:23], 0, v[0:1]
	v_and_b32_e32 v64, 0x70, v3
	v_readfirstlane_b32 s14, v89
	v_add_u32_e32 v92, 0x2000, v89
	v_lshl_add_u64 v[74:75], v[0:1], 0, v[64:65]
	v_add_u32_e32 v0, s1, v2
	s_mov_b32 m0, s14
	v_readfirstlane_b32 s13, v92
	v_add_u32_e32 v91, 0x4000, v89
	v_ashrrev_i32_e32 v1, 31, v0
	s_waitcnt lgkmcnt(0)
	s_barrier
	global_load_lds_dwordx4 v[74:75], off
	v_lshl_add_u64 v[2:3], v[74:75], 0, s[68:69]
	s_mov_b32 m0, s13
	v_readfirstlane_b32 s12, v91
	v_add_u32_e32 v90, 0x6000, v89
	v_lshlrev_b64 v[0:1], 11, v[0:1]
	v_add_u32_e32 v88, 0x8000, v89
	global_load_lds_dwordx4 v[2:3], off
	v_lshl_add_u64 v[2:3], v[74:75], 0, s[10:11]
	s_mov_b32 m0, s12
	v_readfirstlane_b32 s11, v90
	v_lshl_add_u64 v[0:1], s[30:31], 0, v[0:1]
	global_load_lds_dwordx4 v[2:3], off
	v_lshl_add_u64 v[2:3], v[74:75], 0, s[8:9]
	s_mov_b32 m0, s11
	v_readfirstlane_b32 s10, v88
	v_add_u32_e32 v87, 0xa000, v89
	global_load_lds_dwordx4 v[2:3], off
	v_lshl_add_u64 v[76:77], v[0:1], 0, v[64:65]
	s_mov_b32 m0, s10
	v_readfirstlane_b32 s9, v87
	v_add_u32_e32 v99, 0xc000, v89
	global_load_lds_dwordx4 v[76:77], off
	v_lshl_add_u64 v[0:1], v[76:77], 0, s[68:69]
	s_mov_b32 m0, s9
	v_readfirstlane_b32 s16, v99
	v_add_u32_e32 v97, 0xe000, v89
	global_load_lds_dwordx4 v[0:1], off
	v_lshl_add_u64 v[0:1], v[74:75], 0, s[92:93]
	s_mov_b32 m0, s16
	v_readfirstlane_b32 s15, v97
	v_add_u32_e32 v2, 0x10000, v89
	global_load_lds_dwordx4 v[0:1], off
	v_lshl_add_u64 v[0:1], v[74:75], 0, s[60:61]
	s_mov_b32 m0, s15
	v_readfirstlane_b32 s8, v2
	v_add_u32_e32 v2, 0x12000, v89
	global_load_lds_dwordx4 v[0:1], off
	v_lshl_add_u64 v[0:1], v[74:75], 0, s[18:19]
	s_mov_b32 m0, s8
	v_readfirstlane_b32 s7, v2
	v_add_u32_e32 v2, 0x14000, v89
	global_load_lds_dwordx4 v[0:1], off
	v_lshl_add_u64 v[0:1], v[74:75], 0, s[20:21]
	s_mov_b32 m0, s7
	v_readfirstlane_b32 s6, v2
	v_add_u32_e32 v2, 0x16000, v89
	global_load_lds_dwordx4 v[0:1], off
	v_lshl_add_u64 v[0:1], v[76:77], 0, s[92:93]
	s_mov_b32 m0, s6
	v_readfirstlane_b32 s5, v2
	global_load_lds_dwordx4 v[0:1], off
	v_lshl_add_u64 v[0:1], v[76:77], 0, s[60:61]
	s_mov_b32 m0, s5
	v_bfe_u32 v2, v4, 1, 3
	global_load_lds_dwordx4 v[0:1], off
	v_lshrrev_b32_e32 v0, 5, v4
	v_bfe_u32 v1, v4, 5, 1
	v_bitop3_b32 v3, v1, v2, 6 bitop3:0x36
	v_bitop3_b32 v0, v0, v2, 1 bitop3:0x6c
	v_lshlrev_b32_e32 v96, 4, v3
	v_bitop3_b32 v3, v1, v2, 4 bitop3:0x36
	v_bitop3_b32 v1, v1, v2, 2 bitop3:0x36
	v_lshlrev_b32_e32 v106, 4, v0
	v_lshlrev_b32_e32 v0, 7, v4
	v_add_u32_e32 v100, 0x18000, v89
	v_lshlrev_b32_e32 v105, 4, v1
	v_and_b32_e32 v1, 0xf80, v0
	v_and_b32_e32 v108, 0x6f80, v0
	v_lshlrev_b32_e32 v0, 5, v4
	v_readfirstlane_b32 s19, v100
	v_add_u32_e32 v101, 0x1a000, v89
	v_and_or_b32 v107, v0, s35, v1
	v_lshl_add_u64 v[0:1], v[74:75], 0, s[84:85]
	s_mov_b32 m0, s19
	v_readfirstlane_b32 s18, v101
	v_add_u32_e32 v102, 0x1c000, v89
	s_waitcnt vmcnt(6)
	s_barrier
	global_load_lds_dwordx4 v[0:1], off
	v_lshl_add_u64 v[0:1], v[74:75], 0, s[24:25]
	s_mov_b32 m0, s18
	v_readfirstlane_b32 s20, v102
	v_add_u32_e32 v103, 0x1e000, v89
	global_load_lds_dwordx4 v[0:1], off
	v_lshl_add_u64 v[0:1], v[74:75], 0, s[26:27]
	s_mov_b32 m0, s20
	s_mov_b64 s[24:25], 0x60100
	v_readfirstlane_b32 s21, v103
	v_add_u32_e32 v104, 0x20000, v89
	global_load_lds_dwordx4 v[0:1], off
	v_lshl_add_u64 v[0:1], v[74:75], 0, s[24:25]
	s_mov_b32 m0, s21
	v_readfirstlane_b32 s24, v104
	v_add_u32_e32 v98, 0x22000, v89
	global_load_lds_dwordx4 v[0:1], off
	v_lshl_add_u64 v[0:1], v[76:77], 0, s[84:85]
	s_mov_b64 s[26:27], 0x20100
	s_mov_b32 m0, s24
	v_readfirstlane_b32 s17, v98
	global_load_lds_dwordx4 v[0:1], off
	v_lshl_add_u64 v[0:1], v[76:77], 0, s[26:27]
	s_mov_b32 m0, s17
	v_add_u32_e32 v85, 0, v108
	v_add_u32_e32 v86, 0, v107
	global_load_lds_dwordx4 v[0:1], off
	v_add_u32_e32 v80, v85, v106
	v_add_u32_e32 v64, v86, v106
	v_lshlrev_b32_e32 v95, 4, v3
	ds_read_b128 v[4:7], v80
	ds_read_b128 v[0:3], v80 offset:4096
	ds_read_b128 v[8:11], v64 offset:32768
	ds_read_b128 v[12:15], v64 offset:36864
	s_waitcnt lgkmcnt(0)
	v_mfma_f32_32x32x16_bf16 v[48:63], v[8:11], v[4:7], 0
	v_add_u32_e32 v81, v85, v105
	v_add_u32_e32 v82, v86, v105
	ds_read_b128 v[66:69], v81
	ds_read_b128 v[70:73], v81 offset:4096
	ds_read_b128 v[110:113], v82 offset:32768
	ds_read_b128 v[114:117], v82 offset:36864
	v_add_u32_e32 v83, v85, v95
	v_add_u32_e32 v84, v86, v95
	ds_read_b128 v[118:121], v83
	ds_read_b128 v[122:125], v83 offset:4096
	v_mfma_f32_32x32x16_bf16 v[32:47], v[12:15], v[4:7], 0
	ds_read_b128 v[126:129], v84 offset:32768
	ds_read_b128 v[130:133], v84 offset:36864
	v_add_u32_e32 v85, v85, v96
	v_add_u32_e32 v86, v86, v96
	s_mov_b32 m0, s14
	s_mov_b64 s[96:97], 0x60180
	s_add_i32 s25, 0, 0x14000
	v_add_u32_e32 v109, s25, v107
	v_mfma_f32_32x32x16_bf16 v[16:31], v[8:11], v[0:3], 0
	v_add_u32_e32 v93, v109, v106
	v_add_u32_e32 v94, v109, v105
	s_mov_b64 s[62:63], 0x40200
	s_mov_b64 s[90:91], 0x60200
	s_add_i32 s25, 0, 0x18000
	v_add_u32_e32 v140, s25, v108
	v_add_u32_e32 v141, s42, v107
	v_mfma_f32_32x32x16_bf16 v[0:15], v[12:15], v[0:3], 0
	s_mov_b64 s[72:73], 0x40280
	s_mov_b64 s[50:51], 0x60280
	s_mov_b64 s[36:37], 0x20400
	s_mov_b64 s[52:53], 0x40680
	s_add_i32 s0, s0, s70
	s_mov_b64 s[26:27], 0x40100
	s_cmp_ge_i32 s0, s34
	s_waitcnt lgkmcnt(0)
	v_mfma_f32_32x32x16_bf16 v[48:63], v[110:113], v[66:69], v[48:63]
	v_mfma_f32_32x32x16_bf16 v[32:47], v[114:117], v[66:69], v[32:47]
	v_mfma_f32_32x32x16_bf16 v[0:15], v[114:117], v[70:73], v[0:15]
	v_mfma_f32_32x32x16_bf16 v[16:31], v[110:113], v[70:73], v[16:31]
	ds_read_b128 v[66:69], v85
	ds_read_b128 v[70:73], v85 offset:4096
	ds_read_b128 v[110:113], v86 offset:32768
	ds_read_b128 v[114:117], v86 offset:36864
	s_waitcnt vmcnt(6)
	s_barrier
; #define MFMA32(a, b, c) __builtin_amdgcn_mfma_f32_32x32x16_bf16((a), (b), (c), 0, 0, 0)
; template <int NI>
; DEVINL void gemm_kloop(const bf16_t* __restrict__ A, int lda, const bf16_t* __restrict__ Bt, int ldb, int K, int m0, int n0,
;                        unsigned char* lds, f32x16 (&acc)[NI][2]) {
;     ...
;     auto compute = [&](int st_) {
;         const unsigned char* pa = lds + st_ * STAGE + (wm * 64 + r) * 128;
;         const unsigned char* pb = lds + st_ * STAGE + A_ST + (wn * 32 * NI + r) * 128;
;         bf16x8 af[2][2], bfr[2][NI];
; #pragma unroll
;         for (int i = 0; i < 2; ++i) af[0][i] = *(const bf16x8*)(pa + i * 32 * 128 + o4[0]);
; #pragma unroll
;         for (int i = 0; i < NI; ++i) bfr[0][i] = *(const bf16x8*)(pb + i * 32 * 128 + o4[0]);
; #pragma unroll
;         for (int ks = 0; ks < 4; ++ks) {
;             if (ks < 3) {
; #pragma unroll
;                 for (int i = 0; i < 2; ++i) af[(ks + 1) & 1][i] = *(const bf16x8*)(pa + i * 32 * 128 + o4[ks + 1]);
; #pragma unroll
;                 for (int i = 0; i < NI; ++i) bfr[(ks + 1) & 1][i] = *(const bf16x8*)(pb + i * 32 * 128 + o4[ks + 1]);
;             }
; #pragma unroll
;             for (int ni = 0; ni < NI; ++ni)
; #pragma unroll
;                 for (int mi = 0; mi < 2; ++mi) acc[ni][mi] = MFMA32(bfr[ks & 1][ni], af[ks & 1][mi], acc[ni][mi]);
;         }
;     };
;     int t = 0;
;     for (; t + 2 < nt; ++t) {
;         if (NI == 2) asm volatile("s_waitcnt vmcnt(6)" ::: "memory"); else asm volatile("s_waitcnt vmcnt(5)" ::: "memory");
;         __builtin_amdgcn_s_barrier();
;         { const int s2 = (cur >= 1) ? cur - 1 : 2; GEMM_ISSUE(s2, t + 2); }
;         compute(cur);
;         cur = (cur == 2) ? 0 : cur + 1;
;     }
	v_mfma_f32_32x32x16_bf16 v[48:63], v[126:129], v[118:121], v[48:63]
	v_mfma_f32_32x32x16_bf16 v[32:47], v[130:133], v[118:121], v[32:47]
	v_mfma_f32_32x32x16_bf16 v[0:15], v[130:133], v[122:125], v[0:15]
	v_mfma_f32_32x32x16_bf16 v[16:31], v[126:129], v[122:125], v[16:31]
	s_waitcnt lgkmcnt(0)
	v_mfma_f32_32x32x16_bf16 v[48:63], v[110:113], v[66:69], v[48:63]
	v_mfma_f32_32x32x16_bf16 v[32:47], v[114:117], v[66:69], v[32:47]
	v_lshl_add_u64 v[66:67], v[74:75], 0, s[88:89]
	global_load_lds_dwordx4 v[66:67], off
	v_lshl_add_u64 v[66:67], v[74:75], 0, s[56:57]
	s_mov_b32 m0, s13
	s_mov_b64 s[56:57], 0x40180
	global_load_lds_dwordx4 v[66:67], off
	v_lshl_add_u64 v[66:67], v[74:75], 0, s[56:57]
	s_mov_b32 m0, s12
	v_mfma_f32_32x32x16_bf16 v[0:15], v[114:117], v[70:73], v[0:15]
	global_load_lds_dwordx4 v[66:67], off
	v_lshl_add_u64 v[66:67], v[74:75], 0, s[96:97]
	s_mov_b32 m0, s11
	s_mov_b64 s[56:57], 0x20180
	global_load_lds_dwordx4 v[66:67], off
	v_lshl_add_u64 v[66:67], v[76:77], 0, s[88:89]
	s_mov_b32 m0, s10
	v_mfma_f32_32x32x16_bf16 v[16:31], v[110:113], v[70:73], v[16:31]
	global_load_lds_dwordx4 v[66:67], off
	v_lshl_add_u64 v[66:67], v[76:77], 0, s[56:57]
	s_mov_b32 m0, s9
	s_mov_b64 s[96:97], 0x20200
	global_load_lds_dwordx4 v[66:67], off
	ds_read_b128 v[70:73], v80 offset:49152
	ds_read_b128 v[66:69], v80 offset:53248
	ds_read_b128 v[110:113], v93
	ds_read_b128 v[114:117], v93 offset:4096
	ds_read_b128 v[118:121], v81 offset:49152
	ds_read_b128 v[122:125], v81 offset:53248
	s_waitcnt lgkmcnt(0)
	v_mfma_f32_32x32x16_bf16 v[0:15], v[114:117], v[66:69], v[0:15]
	ds_read_b128 v[126:129], v94
	ds_read_b128 v[130:133], v94 offset:4096
	s_mov_b32 m0, s16
	v_mfma_f32_32x32x16_bf16 v[48:63], v[110:113], v[70:73], v[48:63]
	v_mfma_f32_32x32x16_bf16 v[16:31], v[110:113], v[66:69], v[16:31]
	v_add_u32_e32 v66, v109, v95
	v_add_u32_e32 v67, v109, v96
	v_mfma_f32_32x32x16_bf16 v[32:47], v[114:117], v[70:73], v[32:47]
	ds_read_b128 v[68:71], v83 offset:49152
	ds_read_b128 v[110:113], v83 offset:53248
	ds_read_b128 v[114:117], v66
	ds_read_b128 v[134:137], v66 offset:4096
	v_add_u32_e32 v72, v140, v95
	v_add_u32_e32 v73, v141, v95
	v_add_u32_e32 v95, v140, v96
	v_add_u32_e32 v96, v141, v96
	s_waitcnt lgkmcnt(0)
	v_mfma_f32_32x32x16_bf16 v[0:15], v[130:133], v[122:125], v[0:15]
	v_mfma_f32_32x32x16_bf16 v[48:63], v[126:129], v[118:121], v[48:63]
	v_mfma_f32_32x32x16_bf16 v[16:31], v[126:129], v[122:125], v[16:31]
	v_mfma_f32_32x32x16_bf16 v[32:47], v[130:133], v[118:121], v[32:47]
	ds_read_b128 v[118:121], v85 offset:49152
	ds_read_b128 v[122:125], v85 offset:53248
	ds_read_b128 v[126:129], v67
	ds_read_b128 v[130:133], v67 offset:4096
	s_waitcnt vmcnt(6)
	s_barrier
	v_mfma_f32_32x32x16_bf16 v[0:15], v[134:137], v[110:113], v[0:15]
	v_mfma_f32_32x32x16_bf16 v[48:63], v[114:117], v[68:71], v[48:63]
	v_mfma_f32_32x32x16_bf16 v[16:31], v[114:117], v[110:113], v[16:31]
	v_mfma_f32_32x32x16_bf16 v[32:47], v[134:137], v[68:71], v[32:47]
	v_lshl_add_u64 v[68:69], v[74:75], 0, s[58:59]
	global_load_lds_dwordx4 v[68:69], off
	v_lshl_add_u64 v[68:69], v[74:75], 0, s[96:97]
	s_mov_b32 m0, s15
	v_add_u32_e32 v70, v140, v105
	global_load_lds_dwordx4 v[68:69], off
	v_lshl_add_u64 v[68:69], v[74:75], 0, s[62:63]
	s_mov_b32 m0, s8
	s_waitcnt lgkmcnt(0)
	v_mfma_f32_32x32x16_bf16 v[0:15], v[130:133], v[122:125], v[0:15]
	global_load_lds_dwordx4 v[68:69], off
	v_lshl_add_u64 v[68:69], v[74:75], 0, s[90:91]
	s_mov_b32 m0, s7
	v_add_u32_e32 v71, v141, v105
	global_load_lds_dwordx4 v[68:69], off
	v_lshl_add_u64 v[68:69], v[76:77], 0, s[58:59]
	s_mov_b32 m0, s6
	v_mfma_f32_32x32x16_bf16 v[48:63], v[126:129], v[118:121], v[48:63]
	global_load_lds_dwordx4 v[68:69], off
	v_lshl_add_u64 v[68:69], v[76:77], 0, s[96:97]
	s_mov_b32 m0, s5
	s_mov_b64 s[62:63], 0x20280
	global_load_lds_dwordx4 v[68:69], off
	v_add_u32_e32 v68, v140, v106
	v_add_u32_e32 v69, v141, v106
	v_mfma_f32_32x32x16_bf16 v[16:31], v[126:129], v[122:125], v[16:31]
	ds_read_b128 v[108:111], v68
	ds_read_b128 v[112:115], v68 offset:4096
	s_mov_b32 m0, s19
	s_mov_b64 s[90:91], 0x20300
	v_mfma_f32_32x32x16_bf16 v[32:47], v[130:133], v[118:121], v[32:47]
	ds_read_b128 v[116:119], v69
	ds_read_b128 v[120:123], v69 offset:4096
	ds_read_b128 v[124:127], v70
	ds_read_b128 v[128:131], v70 offset:4096
	ds_read_b128 v[132:135], v71
	ds_read_b128 v[136:139], v71 offset:4096
	s_waitcnt lgkmcnt(0)
	v_mfma_f32_32x32x16_bf16 v[0:15], v[120:123], v[112:115], v[0:15]
	v_mfma_f32_32x32x16_bf16 v[48:63], v[116:119], v[108:111], v[48:63]
	v_mfma_f32_32x32x16_bf16 v[16:31], v[116:119], v[112:115], v[16:31]
	v_mfma_f32_32x32x16_bf16 v[32:47], v[120:123], v[108:111], v[32:47]
	ds_read_b128 v[106:109], v72
	ds_read_b128 v[110:113], v72 offset:4096
	ds_read_b128 v[114:117], v73
	ds_read_b128 v[118:121], v73 offset:4096
	v_mfma_f32_32x32x16_bf16 v[0:15], v[136:139], v[128:131], v[0:15]
	v_mfma_f32_32x32x16_bf16 v[48:63], v[132:135], v[124:127], v[48:63]
	v_mfma_f32_32x32x16_bf16 v[16:31], v[132:135], v[128:131], v[16:31]
	v_mfma_f32_32x32x16_bf16 v[32:47], v[136:139], v[124:127], v[32:47]
	ds_read_b128 v[122:125], v95
	ds_read_b128 v[126:129], v95 offset:4096
	ds_read_b128 v[130:133], v96
	ds_read_b128 v[134:137], v96 offset:4096
	s_waitcnt vmcnt(6)
	s_barrier
; #define MFMA32(a, b, c) __builtin_amdgcn_mfma_f32_32x32x16_bf16((a), (b), (c), 0, 0, 0)
; template <int NI>
; DEVINL void gemm_kloop(const bf16_t* __restrict__ A, int lda, const bf16_t* __restrict__ Bt, int ldb, int K, int m0, int n0,
;                        unsigned char* lds, f32x16 (&acc)[NI][2]) {
;     ...
;     auto compute = [&](int st_) {
;         const unsigned char* pa = lds + st_ * STAGE + (wm * 64 + r) * 128;
;         const unsigned char* pb = lds + st_ * STAGE + A_ST + (wn * 32 * NI + r) * 128;
;         bf16x8 af[2][2], bfr[2][NI];
; #pragma unroll
;         for (int i = 0; i < 2; ++i) af[0][i] = *(const bf16x8*)(pa + i * 32 * 128 + o4[0]);
; #pragma unroll
;         for (int i = 0; i < NI; ++i) bfr[0][i] = *(const bf16x8*)(pb + i * 32 * 128 + o4[0]);
; #pragma unroll
;         for (int ks = 0; ks < 4; ++ks) {
;             if (ks < 3) {
; #pragma unroll
;                 for (int i = 0; i < 2; ++i) af[(ks + 1) & 1][i] = *(const bf16x8*)(pa + i * 32 * 128 + o4[ks + 1]);
; #pragma unroll
;                 for (int i = 0; i < NI; ++i) bfr[(ks + 1) & 1][i] = *(const bf16x8*)(pb + i * 32 * 128 + o4[ks + 1]);
;             }
; #pragma unroll
;             for (int ni = 0; ni < NI; ++ni)
; #pragma unroll
;                 for (int mi = 0; mi < 2; ++mi) acc[ni][mi] = MFMA32(bfr[ks & 1][ni], af[ks & 1][mi], acc[ni][mi]);
;         }
;     };
;     int t = 0;
;     for (; t + 2 < nt; ++t) {
;         if (NI == 2) asm volatile("s_waitcnt vmcnt(6)" ::: "memory"); else asm volatile("s_waitcnt vmcnt(5)" ::: "memory");
;         __builtin_amdgcn_s_barrier();
;         { const int s2 = (cur >= 1) ? cur - 1 : 2; GEMM_ISSUE(s2, t + 2); }
;         compute(cur);
;         cur = (cur == 2) ? 0 : cur + 1;
;     }
	s_waitcnt lgkmcnt(0)
	v_mfma_f32_32x32x16_bf16 v[0:15], v[118:121], v[110:113], v[0:15]
	v_mfma_f32_32x32x16_bf16 v[48:63], v[114:117], v[106:109], v[48:63]
	v_mfma_f32_32x32x16_bf16 v[16:31], v[114:117], v[110:113], v[16:31]
	v_mfma_f32_32x32x16_bf16 v[32:47], v[118:121], v[106:109], v[32:47]
	v_lshl_add_u64 v[106:107], v[74:75], 0, s[64:65]
	global_load_lds_dwordx4 v[106:107], off
	v_lshl_add_u64 v[106:107], v[74:75], 0, s[62:63]
	s_mov_b32 m0, s18
	s_nop 0
	global_load_lds_dwordx4 v[106:107], off
	v_mfma_f32_32x32x16_bf16 v[0:15], v[134:137], v[126:129], v[0:15]
	v_lshl_add_u64 v[106:107], v[74:75], 0, s[72:73]
	s_mov_b32 m0, s20
	s_mov_b64 s[72:73], 0x20380
	global_load_lds_dwordx4 v[106:107], off
	v_lshl_add_u64 v[106:107], v[74:75], 0, s[50:51]
	s_mov_b32 m0, s21
	v_mfma_f32_32x32x16_bf16 v[48:63], v[130:133], v[122:125], v[48:63]
	global_load_lds_dwordx4 v[106:107], off
	v_lshl_add_u64 v[106:107], v[76:77], 0, s[64:65]
	s_mov_b32 m0, s24
	s_mov_b64 s[50:51], 0x40300
	global_load_lds_dwordx4 v[106:107], off
	v_lshl_add_u64 v[106:107], v[76:77], 0, s[62:63]
	s_mov_b32 m0, s17
	v_mfma_f32_32x32x16_bf16 v[16:31], v[130:133], v[126:129], v[16:31]
	global_load_lds_dwordx4 v[106:107], off
	s_mov_b32 m0, s14
	v_mfma_f32_32x32x16_bf16 v[32:47], v[134:137], v[122:125], v[32:47]
	ds_read_b128 v[106:109], v80
	ds_read_b128 v[110:113], v80 offset:4096
	ds_read_b128 v[114:117], v64 offset:32768
	ds_read_b128 v[118:121], v64 offset:36864
	ds_read_b128 v[122:125], v81
	ds_read_b128 v[126:129], v81 offset:4096
	ds_read_b128 v[130:133], v82 offset:32768
	ds_read_b128 v[134:137], v82 offset:36864
	s_waitcnt lgkmcnt(0)
	v_mfma_f32_32x32x16_bf16 v[0:15], v[118:121], v[110:113], v[0:15]
	v_mfma_f32_32x32x16_bf16 v[48:63], v[114:117], v[106:109], v[48:63]
	v_mfma_f32_32x32x16_bf16 v[16:31], v[114:117], v[110:113], v[16:31]
	v_mfma_f32_32x32x16_bf16 v[32:47], v[118:121], v[106:109], v[32:47]
	ds_read_b128 v[106:109], v83
	ds_read_b128 v[110:113], v83 offset:4096
	ds_read_b128 v[114:117], v84 offset:32768
	ds_read_b128 v[118:121], v84 offset:36864
	v_mfma_f32_32x32x16_bf16 v[0:15], v[134:137], v[126:129], v[0:15]
	v_mfma_f32_32x32x16_bf16 v[48:63], v[130:133], v[122:125], v[48:63]
	v_mfma_f32_32x32x16_bf16 v[16:31], v[130:133], v[126:129], v[16:31]
	v_mfma_f32_32x32x16_bf16 v[32:47], v[134:137], v[122:125], v[32:47]
	ds_read_b128 v[122:125], v85
	ds_read_b128 v[126:129], v85 offset:4096
	ds_read_b128 v[130:133], v86 offset:32768
	ds_read_b128 v[134:137], v86 offset:36864
	s_waitcnt vmcnt(6)
	s_barrier
	s_waitcnt lgkmcnt(0)
	v_mfma_f32_32x32x16_bf16 v[0:15], v[118:121], v[110:113], v[0:15]
	v_mfma_f32_32x32x16_bf16 v[48:63], v[114:117], v[106:109], v[48:63]
	v_mfma_f32_32x32x16_bf16 v[16:31], v[114:117], v[110:113], v[16:31]
	v_mfma_f32_32x32x16_bf16 v[32:47], v[118:121], v[106:109], v[32:47]
	v_lshl_add_u64 v[106:107], v[74:75], 0, s[2:3]
	global_load_lds_dwordx4 v[106:107], off
	v_lshl_add_u64 v[106:107], v[74:75], 0, s[90:91]
	s_mov_b32 m0, s13
	s_nop 0
	global_load_lds_dwordx4 v[106:107], off
	v_mfma_f32_32x32x16_bf16 v[0:15], v[134:137], v[126:129], v[0:15]
	v_lshl_add_u64 v[106:107], v[74:75], 0, s[50:51]
	s_mov_b64 s[50:51], 0x60300
	s_mov_b32 m0, s12
	s_nop 0
	global_load_lds_dwordx4 v[106:107], off
	v_lshl_add_u64 v[106:107], v[74:75], 0, s[50:51]
	s_mov_b32 m0, s11
	v_mfma_f32_32x32x16_bf16 v[48:63], v[130:133], v[122:125], v[48:63]
	global_load_lds_dwordx4 v[106:107], off
	v_lshl_add_u64 v[106:107], v[76:77], 0, s[2:3]
	s_mov_b32 m0, s10
	s_mov_b64 s[50:51], 0x40380
	global_load_lds_dwordx4 v[106:107], off
	v_lshl_add_u64 v[106:107], v[76:77], 0, s[90:91]
	s_mov_b32 m0, s9
	v_mfma_f32_32x32x16_bf16 v[16:31], v[130:133], v[126:129], v[16:31]
	global_load_lds_dwordx4 v[106:107], off
	s_mov_b32 m0, s16
	v_mfma_f32_32x32x16_bf16 v[32:47], v[134:137], v[122:125], v[32:47]
	ds_read_b128 v[106:109], v80 offset:49152
	ds_read_b128 v[110:113], v80 offset:53248
	ds_read_b128 v[114:117], v93
	ds_read_b128 v[118:121], v93 offset:4096
	ds_read_b128 v[122:125], v81 offset:49152
	ds_read_b128 v[126:129], v81 offset:53248
	ds_read_b128 v[130:133], v94
	ds_read_b128 v[134:137], v94 offset:4096
	s_waitcnt lgkmcnt(0)
	v_mfma_f32_32x32x16_bf16 v[0:15], v[118:121], v[110:113], v[0:15]
	v_mfma_f32_32x32x16_bf16 v[48:63], v[114:117], v[106:109], v[48:63]
	v_mfma_f32_32x32x16_bf16 v[16:31], v[114:117], v[110:113], v[16:31]
	v_mfma_f32_32x32x16_bf16 v[32:47], v[118:121], v[106:109], v[32:47]
	ds_read_b128 v[106:109], v83 offset:49152
	ds_read_b128 v[110:113], v83 offset:53248
	ds_read_b128 v[114:117], v66
	ds_read_b128 v[118:121], v66 offset:4096
	v_mfma_f32_32x32x16_bf16 v[0:15], v[134:137], v[126:129], v[0:15]
	v_mfma_f32_32x32x16_bf16 v[48:63], v[130:133], v[122:125], v[48:63]
	v_mfma_f32_32x32x16_bf16 v[16:31], v[130:133], v[126:129], v[16:31]
	v_mfma_f32_32x32x16_bf16 v[32:47], v[134:137], v[122:125], v[32:47]
	ds_read_b128 v[122:125], v85 offset:49152
	ds_read_b128 v[126:129], v85 offset:53248
	ds_read_b128 v[130:133], v67
	ds_read_b128 v[134:137], v67 offset:4096
	s_waitcnt vmcnt(6)
	s_barrier
; #define MFMA32(a, b, c) __builtin_amdgcn_mfma_f32_32x32x16_bf16((a), (b), (c), 0, 0, 0)
; template <int NI>
; DEVINL void gemm_kloop(const bf16_t* __restrict__ A, int lda, const bf16_t* __restrict__ Bt, int ldb, int K, int m0, int n0,
;                        unsigned char* lds, f32x16 (&acc)[NI][2]) {
;     ...
;     auto compute = [&](int st_) {
;         const unsigned char* pa = lds + st_ * STAGE + (wm * 64 + r) * 128;
;         const unsigned char* pb = lds + st_ * STAGE + A_ST + (wn * 32 * NI + r) * 128;
;         bf16x8 af[2][2], bfr[2][NI];
; #pragma unroll
;         for (int i = 0; i < 2; ++i) af[0][i] = *(const bf16x8*)(pa + i * 32 * 128 + o4[0]);
; #pragma unroll
;         for (int i = 0; i < NI; ++i) bfr[0][i] = *(const bf16x8*)(pb + i * 32 * 128 + o4[0]);
; #pragma unroll
;         for (int ks = 0; ks < 4; ++ks) {
;             if (ks < 3) {
; #pragma unroll
;                 for (int i = 0; i < 2; ++i) af[(ks + 1) & 1][i] = *(const bf16x8*)(pa + i * 32 * 128 + o4[ks + 1]);
; #pragma unroll
;                 for (int i = 0; i < NI; ++i) bfr[(ks + 1) & 1][i] = *(const bf16x8*)(pb + i * 32 * 128 + o4[ks + 1]);
;             }
; #pragma unroll
;             for (int ni = 0; ni < NI; ++ni)
; #pragma unroll
;                 for (int mi = 0; mi < 2; ++mi) acc[ni][mi] = MFMA32(bfr[ks & 1][ni], af[ks & 1][mi], acc[ni][mi]);
;         }
;     };
;     int t = 0;
;     for (; t + 2 < nt; ++t) {
;         if (NI == 2) asm volatile("s_waitcnt vmcnt(6)" ::: "memory"); else asm volatile("s_waitcnt vmcnt(5)" ::: "memory");
;         __builtin_amdgcn_s_barrier();
;         { const int s2 = (cur >= 1) ? cur - 1 : 2; GEMM_ISSUE(s2, t + 2); }
;         compute(cur);
;         cur = (cur == 2) ? 0 : cur + 1;
;     }
	s_waitcnt lgkmcnt(0)
	v_mfma_f32_32x32x16_bf16 v[0:15], v[118:121], v[110:113], v[0:15]
	v_mfma_f32_32x32x16_bf16 v[48:63], v[114:117], v[106:109], v[48:63]
	v_mfma_f32_32x32x16_bf16 v[16:31], v[114:117], v[110:113], v[16:31]
	v_mfma_f32_32x32x16_bf16 v[32:47], v[118:121], v[106:109], v[32:47]
	v_lshl_add_u64 v[106:107], v[74:75], 0, s[40:41]
	global_load_lds_dwordx4 v[106:107], off
	v_lshl_add_u64 v[106:107], v[74:75], 0, s[72:73]
	s_mov_b32 m0, s15
	s_nop 0
	global_load_lds_dwordx4 v[106:107], off
	v_mfma_f32_32x32x16_bf16 v[0:15], v[134:137], v[126:129], v[0:15]
	v_lshl_add_u64 v[106:107], v[74:75], 0, s[50:51]
	s_mov_b64 s[50:51], 0x60380
	s_mov_b32 m0, s8
	s_nop 0
	global_load_lds_dwordx4 v[106:107], off
	v_lshl_add_u64 v[106:107], v[74:75], 0, s[50:51]
	s_mov_b32 m0, s7
	v_mfma_f32_32x32x16_bf16 v[48:63], v[130:133], v[122:125], v[48:63]
	global_load_lds_dwordx4 v[106:107], off
	v_lshl_add_u64 v[106:107], v[76:77], 0, s[40:41]
	s_mov_b32 m0, s6
	s_mov_b64 s[50:51], 0x400
	global_load_lds_dwordx4 v[106:107], off
	v_lshl_add_u64 v[106:107], v[76:77], 0, s[72:73]
	s_mov_b32 m0, s5
	v_mfma_f32_32x32x16_bf16 v[16:31], v[130:133], v[126:129], v[16:31]
	global_load_lds_dwordx4 v[106:107], off
	s_mov_b32 m0, s19
	v_mfma_f32_32x32x16_bf16 v[32:47], v[134:137], v[122:125], v[32:47]
	ds_read_b128 v[106:109], v68
	ds_read_b128 v[110:113], v68 offset:4096
	ds_read_b128 v[114:117], v69
	ds_read_b128 v[118:121], v69 offset:4096
	ds_read_b128 v[122:125], v70
	ds_read_b128 v[126:129], v70 offset:4096
	ds_read_b128 v[130:133], v71
	ds_read_b128 v[134:137], v71 offset:4096
	s_waitcnt lgkmcnt(0)
	v_mfma_f32_32x32x16_bf16 v[0:15], v[118:121], v[110:113], v[0:15]
	v_mfma_f32_32x32x16_bf16 v[48:63], v[114:117], v[106:109], v[48:63]
	v_mfma_f32_32x32x16_bf16 v[16:31], v[114:117], v[110:113], v[16:31]
	v_mfma_f32_32x32x16_bf16 v[32:47], v[118:121], v[106:109], v[32:47]
	ds_read_b128 v[106:109], v72
	ds_read_b128 v[110:113], v72 offset:4096
	ds_read_b128 v[114:117], v73
	ds_read_b128 v[118:121], v73 offset:4096
	v_mfma_f32_32x32x16_bf16 v[0:15], v[134:137], v[126:129], v[0:15]
	v_mfma_f32_32x32x16_bf16 v[48:63], v[130:133], v[122:125], v[48:63]
	v_mfma_f32_32x32x16_bf16 v[16:31], v[130:133], v[126:129], v[16:31]
	v_mfma_f32_32x32x16_bf16 v[32:47], v[134:137], v[122:125], v[32:47]
	ds_read_b128 v[122:125], v95
	ds_read_b128 v[126:129], v95 offset:4096
	ds_read_b128 v[130:133], v96
	ds_read_b128 v[134:137], v96 offset:4096
	s_waitcnt vmcnt(6)
	s_barrier
	s_waitcnt lgkmcnt(0)
	v_mfma_f32_32x32x16_bf16 v[0:15], v[118:121], v[110:113], v[0:15]
	v_mfma_f32_32x32x16_bf16 v[48:63], v[114:117], v[106:109], v[48:63]
	v_mfma_f32_32x32x16_bf16 v[16:31], v[114:117], v[110:113], v[16:31]
	v_mfma_f32_32x32x16_bf16 v[32:47], v[118:121], v[106:109], v[32:47]
	v_lshl_add_u64 v[106:107], v[74:75], 0, s[50:51]
	global_load_lds_dwordx4 v[106:107], off
	v_lshl_add_u64 v[106:107], v[74:75], 0, s[36:37]
	s_mov_b64 s[36:37], 0x40400
	s_mov_b32 m0, s18
	s_mov_b64 s[18:19], 0x60400
	v_mfma_f32_32x32x16_bf16 v[0:15], v[134:137], v[126:129], v[0:15]
	global_load_lds_dwordx4 v[106:107], off
	v_lshl_add_u64 v[106:107], v[74:75], 0, s[36:37]
	s_mov_b32 m0, s20
	s_mov_b64 s[36:37], 0x480
	global_load_lds_dwordx4 v[106:107], off
	v_lshl_add_u64 v[106:107], v[74:75], 0, s[18:19]
	s_mov_b32 m0, s21
	s_mov_b64 s[18:19], 0x20400
	global_load_lds_dwordx4 v[106:107], off
	v_lshl_add_u64 v[106:107], v[76:77], 0, s[50:51]
	s_mov_b32 m0, s24
	v_mfma_f32_32x32x16_bf16 v[48:63], v[130:133], v[122:125], v[48:63]
	global_load_lds_dwordx4 v[106:107], off
	v_lshl_add_u64 v[106:107], v[76:77], 0, s[18:19]
	s_mov_b32 m0, s17
	s_mov_b64 s[20:21], 0x20480
	global_load_lds_dwordx4 v[106:107], off
	v_mfma_f32_32x32x16_bf16 v[16:31], v[130:133], v[126:129], v[16:31]
	s_mov_b32 m0, s14
	s_mov_b64 s[50:51], 0x40480
	s_mov_b64 s[14:15], 0x60480
	s_mov_b64 s[16:17], 0x40500
	s_mov_b64 s[18:19], 0x60500
	s_mov_b64 s[24:25], 0x580
	v_mfma_f32_32x32x16_bf16 v[32:47], v[134:137], v[122:125], v[32:47]
	ds_read_b128 v[106:109], v80
	ds_read_b128 v[110:113], v80 offset:4096
	ds_read_b128 v[114:117], v64 offset:32768
	ds_read_b128 v[118:121], v64 offset:36864
	ds_read_b128 v[122:125], v81
	ds_read_b128 v[126:129], v81 offset:4096
	ds_read_b128 v[130:133], v82 offset:32768
	ds_read_b128 v[134:137], v82 offset:36864
	s_waitcnt lgkmcnt(0)
	v_mfma_f32_32x32x16_bf16 v[0:15], v[118:121], v[110:113], v[0:15]
	v_mfma_f32_32x32x16_bf16 v[48:63], v[114:117], v[106:109], v[48:63]
	v_mfma_f32_32x32x16_bf16 v[16:31], v[114:117], v[110:113], v[16:31]
	v_mfma_f32_32x32x16_bf16 v[32:47], v[118:121], v[106:109], v[32:47]
	ds_read_b128 v[106:109], v83
	ds_read_b128 v[110:113], v83 offset:4096
	ds_read_b128 v[114:117], v84 offset:32768
	ds_read_b128 v[118:121], v84 offset:36864
	v_mfma_f32_32x32x16_bf16 v[0:15], v[134:137], v[126:129], v[0:15]
	v_mfma_f32_32x32x16_bf16 v[48:63], v[130:133], v[122:125], v[48:63]
	v_mfma_f32_32x32x16_bf16 v[16:31], v[130:133], v[126:129], v[16:31]
	v_mfma_f32_32x32x16_bf16 v[32:47], v[134:137], v[122:125], v[32:47]
	ds_read_b128 v[122:125], v85
	ds_read_b128 v[126:129], v85 offset:4096
	ds_read_b128 v[130:133], v86 offset:32768
	ds_read_b128 v[134:137], v86 offset:36864
	s_waitcnt vmcnt(6)
	s_barrier
; #define MFMA32(a, b, c) __builtin_amdgcn_mfma_f32_32x32x16_bf16((a), (b), (c), 0, 0, 0)
; template <int NI>
; DEVINL void gemm_kloop(const bf16_t* __restrict__ A, int lda, const bf16_t* __restrict__ Bt, int ldb, int K, int m0, int n0,
;                        unsigned char* lds, f32x16 (&acc)[NI][2]) {
;     ...
;     auto compute = [&](int st_) {
;         const unsigned char* pa = lds + st_ * STAGE + (wm * 64 + r) * 128;
;         const unsigned char* pb = lds + st_ * STAGE + A_ST + (wn * 32 * NI + r) * 128;
;         bf16x8 af[2][2], bfr[2][NI];
; #pragma unroll
;         for (int i = 0; i < 2; ++i) af[0][i] = *(const bf16x8*)(pa + i * 32 * 128 + o4[0]);
; #pragma unroll
;         for (int i = 0; i < NI; ++i) bfr[0][i] = *(const bf16x8*)(pb + i * 32 * 128 + o4[0]);
; #pragma unroll
;         for (int ks = 0; ks < 4; ++ks) {
;             if (ks < 3) {
; #pragma unroll
;                 for (int i = 0; i < 2; ++i) af[(ks + 1) & 1][i] = *(const bf16x8*)(pa + i * 32 * 128 + o4[ks + 1]);
; #pragma unroll
;                 for (int i = 0; i < NI; ++i) bfr[(ks + 1) & 1][i] = *(const bf16x8*)(pb + i * 32 * 128 + o4[ks + 1]);
;             }
; #pragma unroll
;             for (int ni = 0; ni < NI; ++ni)
; #pragma unroll
;                 for (int mi = 0; mi < 2; ++mi) acc[ni][mi] = MFMA32(bfr[ks & 1][ni], af[ks & 1][mi], acc[ni][mi]);
;         }
;     };
;     int t = 0;
;     for (; t + 2 < nt; ++t) {
;         if (NI == 2) asm volatile("s_waitcnt vmcnt(6)" ::: "memory"); else asm volatile("s_waitcnt vmcnt(5)" ::: "memory");
;         __builtin_amdgcn_s_barrier();
;         { const int s2 = (cur >= 1) ? cur - 1 : 2; GEMM_ISSUE(s2, t + 2); }
;         compute(cur);
;         cur = (cur == 2) ? 0 : cur + 1;
;     }
	s_waitcnt lgkmcnt(0)
	v_mfma_f32_32x32x16_bf16 v[0:15], v[118:121], v[110:113], v[0:15]
	v_mfma_f32_32x32x16_bf16 v[48:63], v[114:117], v[106:109], v[48:63]
	v_mfma_f32_32x32x16_bf16 v[16:31], v[114:117], v[110:113], v[16:31]
	v_mfma_f32_32x32x16_bf16 v[32:47], v[118:121], v[106:109], v[32:47]
	v_lshl_add_u64 v[106:107], v[74:75], 0, s[36:37]
	global_load_lds_dwordx4 v[106:107], off
	v_lshl_add_u64 v[106:107], v[74:75], 0, s[20:21]
	s_mov_b32 m0, s13
	s_nop 0
	global_load_lds_dwordx4 v[106:107], off
	v_mfma_f32_32x32x16_bf16 v[0:15], v[134:137], v[126:129], v[0:15]
	v_lshl_add_u64 v[106:107], v[74:75], 0, s[50:51]
	s_mov_b32 m0, s12
	s_mov_b64 s[12:13], 0x500
	global_load_lds_dwordx4 v[106:107], off
	v_lshl_add_u64 v[106:107], v[74:75], 0, s[14:15]
	s_mov_b32 m0, s11
	v_mfma_f32_32x32x16_bf16 v[48:63], v[130:133], v[122:125], v[48:63]
	global_load_lds_dwordx4 v[106:107], off
	v_lshl_add_u64 v[106:107], v[76:77], 0, s[36:37]
	s_mov_b32 m0, s10
	v_readfirstlane_b32 s10, v99
	global_load_lds_dwordx4 v[106:107], off
	v_lshl_add_u64 v[106:107], v[76:77], 0, s[20:21]
	s_mov_b32 m0, s9
	v_mfma_f32_32x32x16_bf16 v[16:31], v[130:133], v[126:129], v[16:31]
	global_load_lds_dwordx4 v[106:107], off
	s_mov_b64 s[14:15], 0x20500
	s_mov_b32 m0, s10
	v_readfirstlane_b32 s9, v97
	s_mov_b64 s[36:37], 0x20580
	v_readfirstlane_b32 s11, v101
	v_mfma_f32_32x32x16_bf16 v[32:47], v[134:137], v[122:125], v[32:47]
	ds_read_b128 v[106:109], v80 offset:49152
	ds_read_b128 v[110:113], v80 offset:53248
	ds_read_b128 v[114:117], v93
	ds_read_b128 v[118:121], v93 offset:4096
	ds_read_b128 v[122:125], v81 offset:49152
	ds_read_b128 v[126:129], v81 offset:53248
	ds_read_b128 v[130:133], v94
	ds_read_b128 v[134:137], v94 offset:4096
	s_mov_b64 s[50:51], 0x40580
	v_readfirstlane_b32 s20, v98
	v_readfirstlane_b32 s21, v89
	s_waitcnt lgkmcnt(0)
	v_mfma_f32_32x32x16_bf16 v[0:15], v[118:121], v[110:113], v[0:15]
	v_mfma_f32_32x32x16_bf16 v[48:63], v[114:117], v[106:109], v[48:63]
	v_mfma_f32_32x32x16_bf16 v[16:31], v[114:117], v[110:113], v[16:31]
	v_mfma_f32_32x32x16_bf16 v[32:47], v[118:121], v[106:109], v[32:47]
	ds_read_b128 v[106:109], v83 offset:49152
	ds_read_b128 v[110:113], v83 offset:53248
	ds_read_b128 v[114:117], v66
	ds_read_b128 v[118:121], v66 offset:4096
	v_mfma_f32_32x32x16_bf16 v[0:15], v[134:137], v[126:129], v[0:15]
	v_mfma_f32_32x32x16_bf16 v[48:63], v[130:133], v[122:125], v[48:63]
	v_mfma_f32_32x32x16_bf16 v[16:31], v[130:133], v[126:129], v[16:31]
	v_mfma_f32_32x32x16_bf16 v[32:47], v[134:137], v[122:125], v[32:47]
	ds_read_b128 v[122:125], v85 offset:49152
	ds_read_b128 v[126:129], v85 offset:53248
	ds_read_b128 v[130:133], v67
	ds_read_b128 v[134:137], v67 offset:4096
	s_waitcnt vmcnt(6)
	s_barrier
	s_waitcnt lgkmcnt(0)
	v_mfma_f32_32x32x16_bf16 v[0:15], v[118:121], v[110:113], v[0:15]
	v_mfma_f32_32x32x16_bf16 v[48:63], v[114:117], v[106:109], v[48:63]
	v_mfma_f32_32x32x16_bf16 v[16:31], v[114:117], v[110:113], v[16:31]
	v_mfma_f32_32x32x16_bf16 v[32:47], v[118:121], v[106:109], v[32:47]
	v_lshl_add_u64 v[106:107], v[74:75], 0, s[12:13]
	global_load_lds_dwordx4 v[106:107], off
	v_lshl_add_u64 v[106:107], v[74:75], 0, s[14:15]
	s_mov_b32 m0, s9
	s_nop 0
	global_load_lds_dwordx4 v[106:107], off
	v_mfma_f32_32x32x16_bf16 v[0:15], v[134:137], v[126:129], v[0:15]
	v_lshl_add_u64 v[106:107], v[74:75], 0, s[16:17]
	s_mov_b32 m0, s8
	s_mov_b64 s[16:17], 0x60580
	global_load_lds_dwordx4 v[106:107], off
	v_lshl_add_u64 v[106:107], v[74:75], 0, s[18:19]
	s_mov_b32 m0, s7
	v_mfma_f32_32x32x16_bf16 v[48:63], v[130:133], v[122:125], v[48:63]
	global_load_lds_dwordx4 v[106:107], off
	v_lshl_add_u64 v[106:107], v[76:77], 0, s[12:13]
	s_mov_b32 m0, s6
	v_readfirstlane_b32 s12, v102
	global_load_lds_dwordx4 v[106:107], off
	v_lshl_add_u64 v[106:107], v[76:77], 0, s[14:15]
	s_mov_b32 m0, s5
	v_mfma_f32_32x32x16_bf16 v[16:31], v[130:133], v[126:129], v[16:31]
	global_load_lds_dwordx4 v[106:107], off
	v_readfirstlane_b32 s15, v100
	s_mov_b32 m0, s15
	v_lshl_add_u64 v[100:101], v[74:75], 0, s[50:51]
	v_readfirstlane_b32 s13, v103
	v_readfirstlane_b32 s14, v104
	v_mfma_f32_32x32x16_bf16 v[32:47], v[134:137], v[122:125], v[32:47]
	ds_read_b128 v[106:109], v68
	ds_read_b128 v[110:113], v68 offset:4096
	ds_read_b128 v[114:117], v69
	ds_read_b128 v[118:121], v69 offset:4096
	ds_read_b128 v[122:125], v70
	ds_read_b128 v[126:129], v70 offset:4096
	ds_read_b128 v[130:133], v71
	ds_read_b128 v[134:137], v71 offset:4096
	s_mov_b64 s[18:19], 0x40600
	s_mov_b64 s[50:51], 0x60600
	s_waitcnt lgkmcnt(0)
	v_mfma_f32_32x32x16_bf16 v[0:15], v[118:121], v[110:113], v[0:15]
	v_mfma_f32_32x32x16_bf16 v[48:63], v[114:117], v[106:109], v[48:63]
	v_mfma_f32_32x32x16_bf16 v[16:31], v[114:117], v[110:113], v[16:31]
	v_mfma_f32_32x32x16_bf16 v[32:47], v[118:121], v[106:109], v[32:47]
	ds_read_b128 v[106:109], v72
	ds_read_b128 v[110:113], v72 offset:4096
	ds_read_b128 v[114:117], v73
	ds_read_b128 v[118:121], v73 offset:4096
	v_mfma_f32_32x32x16_bf16 v[0:15], v[134:137], v[126:129], v[0:15]
	v_mfma_f32_32x32x16_bf16 v[48:63], v[130:133], v[122:125], v[48:63]
	v_mfma_f32_32x32x16_bf16 v[16:31], v[130:133], v[126:129], v[16:31]
	v_mfma_f32_32x32x16_bf16 v[32:47], v[134:137], v[122:125], v[32:47]
	ds_read_b128 v[122:125], v95
	ds_read_b128 v[126:129], v95 offset:4096
	ds_read_b128 v[130:133], v96
	ds_read_b128 v[134:137], v96 offset:4096
	s_waitcnt vmcnt(6)
	s_barrier
; #define MFMA32(a, b, c) __builtin_amdgcn_mfma_f32_32x32x16_bf16((a), (b), (c), 0, 0, 0)
; template <int NI>
; DEVINL void gemm_kloop(const bf16_t* __restrict__ A, int lda, const bf16_t* __restrict__ Bt, int ldb, int K, int m0, int n0,
;                        unsigned char* lds, f32x16 (&acc)[NI][2]) {
;     ...
;     auto compute = [&](int st_) {
;         const unsigned char* pa = lds + st_ * STAGE + (wm * 64 + r) * 128;
;         const unsigned char* pb = lds + st_ * STAGE + A_ST + (wn * 32 * NI + r) * 128;
;         bf16x8 af[2][2], bfr[2][NI];
; #pragma unroll
;         for (int i = 0; i < 2; ++i) af[0][i] = *(const bf16x8*)(pa + i * 32 * 128 + o4[0]);
; #pragma unroll
;         for (int i = 0; i < NI; ++i) bfr[0][i] = *(const bf16x8*)(pb + i * 32 * 128 + o4[0]);
; #pragma unroll
;         for (int ks = 0; ks < 4; ++ks) {
;             if (ks < 3) {
; #pragma unroll
;                 for (int i = 0; i < 2; ++i) af[(ks + 1) & 1][i] = *(const bf16x8*)(pa + i * 32 * 128 + o4[ks + 1]);
; #pragma unroll
;                 for (int i = 0; i < NI; ++i) bfr[(ks + 1) & 1][i] = *(const bf16x8*)(pb + i * 32 * 128 + o4[ks + 1]);
;             }
; #pragma unroll
;             for (int ni = 0; ni < NI; ++ni)
; #pragma unroll
;                 for (int mi = 0; mi < 2; ++mi) acc[ni][mi] = MFMA32(bfr[ks & 1][ni], af[ks & 1][mi], acc[ni][mi]);
;         }
;     };
;     int t = 0;
;     for (; t + 2 < nt; ++t) {
;         if (NI == 2) asm volatile("s_waitcnt vmcnt(6)" ::: "memory"); else asm volatile("s_waitcnt vmcnt(5)" ::: "memory");
;         __builtin_amdgcn_s_barrier();
;         { const int s2 = (cur >= 1) ? cur - 1 : 2; GEMM_ISSUE(s2, t + 2); }
;         compute(cur);
;         cur = (cur == 2) ? 0 : cur + 1;
;     }
	s_waitcnt lgkmcnt(0)
	v_mfma_f32_32x32x16_bf16 v[0:15], v[118:121], v[110:113], v[0:15]
	v_mfma_f32_32x32x16_bf16 v[48:63], v[114:117], v[106:109], v[48:63]
	v_mfma_f32_32x32x16_bf16 v[16:31], v[114:117], v[110:113], v[16:31]
	v_mfma_f32_32x32x16_bf16 v[32:47], v[118:121], v[106:109], v[32:47]
	v_lshl_add_u64 v[106:107], v[74:75], 0, s[24:25]
	global_load_lds_dwordx4 v[106:107], off
	v_lshl_add_u64 v[106:107], v[74:75], 0, s[36:37]
	s_mov_b32 m0, s11
	s_nop 0
	global_load_lds_dwordx4 v[106:107], off
	v_mfma_f32_32x32x16_bf16 v[0:15], v[134:137], v[126:129], v[0:15]
	s_mov_b32 m0, s12
	s_nop 0
	global_load_lds_dwordx4 v[100:101], off
	v_lshl_add_u64 v[100:101], v[74:75], 0, s[16:17]
	s_mov_b32 m0, s13
	v_readfirstlane_b32 s16, v92
	global_load_lds_dwordx4 v[100:101], off
	v_lshl_add_u64 v[100:101], v[76:77], 0, s[24:25]
	s_mov_b32 m0, s14
	v_mfma_f32_32x32x16_bf16 v[48:63], v[130:133], v[122:125], v[48:63]
	global_load_lds_dwordx4 v[100:101], off
	v_lshl_add_u64 v[100:101], v[76:77], 0, s[36:37]
	s_mov_b32 m0, s20
	s_mov_b64 s[24:25], 0x600
	global_load_lds_dwordx4 v[100:101], off
	v_mfma_f32_32x32x16_bf16 v[16:31], v[130:133], v[126:129], v[16:31]
	s_mov_b64 s[36:37], 0x20600
	s_mov_b32 m0, s21
	v_readfirstlane_b32 s17, v91
	v_mfma_f32_32x32x16_bf16 v[32:47], v[134:137], v[122:125], v[32:47]
	ds_read_b128 v[98:101], v80
	ds_read_b128 v[102:105], v80 offset:4096
	ds_read_b128 v[106:109], v64 offset:32768
	ds_read_b128 v[110:113], v64 offset:36864
	ds_read_b128 v[114:117], v81
	ds_read_b128 v[118:121], v81 offset:4096
	ds_read_b128 v[122:125], v82 offset:32768
	ds_read_b128 v[126:129], v82 offset:36864
	s_waitcnt lgkmcnt(0)
	v_mfma_f32_32x32x16_bf16 v[0:15], v[110:113], v[102:105], v[0:15]
	v_mfma_f32_32x32x16_bf16 v[48:63], v[106:109], v[98:101], v[48:63]
	v_mfma_f32_32x32x16_bf16 v[16:31], v[106:109], v[102:105], v[16:31]
	v_mfma_f32_32x32x16_bf16 v[32:47], v[110:113], v[98:101], v[32:47]
	ds_read_b128 v[98:101], v83
	ds_read_b128 v[102:105], v83 offset:4096
	ds_read_b128 v[106:109], v84 offset:32768
	ds_read_b128 v[110:113], v84 offset:36864
	v_mfma_f32_32x32x16_bf16 v[0:15], v[126:129], v[118:121], v[0:15]
	v_mfma_f32_32x32x16_bf16 v[48:63], v[122:125], v[114:117], v[48:63]
	v_mfma_f32_32x32x16_bf16 v[16:31], v[122:125], v[118:121], v[16:31]
	v_mfma_f32_32x32x16_bf16 v[32:47], v[126:129], v[114:117], v[32:47]
	ds_read_b128 v[114:117], v85
	ds_read_b128 v[118:121], v85 offset:4096
	ds_read_b128 v[122:125], v86 offset:32768
	ds_read_b128 v[126:129], v86 offset:36864
	s_waitcnt vmcnt(6)
	s_barrier
	s_waitcnt lgkmcnt(0)
	v_mfma_f32_32x32x16_bf16 v[0:15], v[110:113], v[102:105], v[0:15]
	v_mfma_f32_32x32x16_bf16 v[48:63], v[106:109], v[98:101], v[48:63]
	v_mfma_f32_32x32x16_bf16 v[16:31], v[106:109], v[102:105], v[16:31]
	v_mfma_f32_32x32x16_bf16 v[32:47], v[110:113], v[98:101], v[32:47]
	v_lshl_add_u64 v[98:99], v[74:75], 0, s[24:25]
	global_load_lds_dwordx4 v[98:99], off
	v_lshl_add_u64 v[98:99], v[74:75], 0, s[36:37]
	s_mov_b32 m0, s16
	s_nop 0
	global_load_lds_dwordx4 v[98:99], off
	v_mfma_f32_32x32x16_bf16 v[0:15], v[126:129], v[118:121], v[0:15]
	v_lshl_add_u64 v[98:99], v[74:75], 0, s[18:19]
	s_mov_b32 m0, s17
	v_readfirstlane_b32 s18, v90
	global_load_lds_dwordx4 v[98:99], off
	v_lshl_add_u64 v[98:99], v[74:75], 0, s[50:51]
	s_mov_b32 m0, s18
	v_readfirstlane_b32 s19, v88
	global_load_lds_dwordx4 v[98:99], off
	v_lshl_add_u64 v[90:91], v[76:77], 0, s[24:25]
	s_mov_b32 m0, s19
	v_readfirstlane_b32 s24, v87
	global_load_lds_dwordx4 v[90:91], off
	v_lshl_add_u64 v[88:89], v[76:77], 0, s[36:37]
	s_mov_b32 m0, s24
	v_mfma_f32_32x32x16_bf16 v[48:63], v[122:125], v[114:117], v[48:63]
	global_load_lds_dwordx4 v[88:89], off
	s_mov_b64 s[36:37], 0x680
	s_mov_b64 s[50:51], 0x20680
	s_mov_b32 m0, s10
	v_mfma_f32_32x32x16_bf16 v[16:31], v[122:125], v[118:121], v[16:31]
	v_mfma_f32_32x32x16_bf16 v[32:47], v[126:129], v[114:117], v[32:47]
	ds_read_b128 v[88:91], v80 offset:49152
	ds_read_b128 v[98:101], v80 offset:53248
	ds_read_b128 v[102:105], v93
	ds_read_b128 v[106:109], v93 offset:4096
	ds_read_b128 v[110:113], v81 offset:49152
	ds_read_b128 v[114:117], v81 offset:53248
	ds_read_b128 v[118:121], v94
	ds_read_b128 v[122:125], v94 offset:4096
	s_waitcnt lgkmcnt(0)
	v_mfma_f32_32x32x16_bf16 v[0:15], v[106:109], v[98:101], v[0:15]
	v_mfma_f32_32x32x16_bf16 v[48:63], v[102:105], v[88:91], v[48:63]
	v_mfma_f32_32x32x16_bf16 v[16:31], v[102:105], v[98:101], v[16:31]
	v_mfma_f32_32x32x16_bf16 v[32:47], v[106:109], v[88:91], v[32:47]
	ds_read_b128 v[88:91], v83 offset:49152
	ds_read_b128 v[98:101], v83 offset:53248
	ds_read_b128 v[102:105], v66
	ds_read_b128 v[106:109], v66 offset:4096
	v_mfma_f32_32x32x16_bf16 v[0:15], v[122:125], v[114:117], v[0:15]
	v_mfma_f32_32x32x16_bf16 v[48:63], v[118:121], v[110:113], v[48:63]
	v_mfma_f32_32x32x16_bf16 v[16:31], v[118:121], v[114:117], v[16:31]
	v_mfma_f32_32x32x16_bf16 v[32:47], v[122:125], v[110:113], v[32:47]
	ds_read_b128 v[110:113], v85 offset:49152
	ds_read_b128 v[114:117], v85 offset:53248
	ds_read_b128 v[118:121], v67
	ds_read_b128 v[122:125], v67 offset:4096
	s_waitcnt vmcnt(6)
	s_barrier
; #define MFMA32(a, b, c) __builtin_amdgcn_mfma_f32_32x32x16_bf16((a), (b), (c), 0, 0, 0)
; template <int NI>
; DEVINL void gemm_kloop(const bf16_t* __restrict__ A, int lda, const bf16_t* __restrict__ Bt, int ldb, int K, int m0, int n0,
;                        unsigned char* lds, f32x16 (&acc)[NI][2]) {
;     ...
;     auto compute = [&](int st_) {
;         const unsigned char* pa = lds + st_ * STAGE + (wm * 64 + r) * 128;
;         const unsigned char* pb = lds + st_ * STAGE + A_ST + (wn * 32 * NI + r) * 128;
;         bf16x8 af[2][2], bfr[2][NI];
; #pragma unroll
;         for (int i = 0; i < 2; ++i) af[0][i] = *(const bf16x8*)(pa + i * 32 * 128 + o4[0]);
; #pragma unroll
;         for (int i = 0; i < NI; ++i) bfr[0][i] = *(const bf16x8*)(pb + i * 32 * 128 + o4[0]);
; #pragma unroll
;         for (int ks = 0; ks < 4; ++ks) {
;             if (ks < 3) {
; #pragma unroll
;                 for (int i = 0; i < 2; ++i) af[(ks + 1) & 1][i] = *(const bf16x8*)(pa + i * 32 * 128 + o4[ks + 1]);
; #pragma unroll
;                 for (int i = 0; i < NI; ++i) bfr[(ks + 1) & 1][i] = *(const bf16x8*)(pb + i * 32 * 128 + o4[ks + 1]);
;             }
; #pragma unroll
;             for (int ni = 0; ni < NI; ++ni)
; #pragma unroll
;                 for (int mi = 0; mi < 2; ++mi) acc[ni][mi] = MFMA32(bfr[ks & 1][ni], af[ks & 1][mi], acc[ni][mi]);
;         }
;     };
;     int t = 0;
;     for (; t + 2 < nt; ++t) {
;         if (NI == 2) asm volatile("s_waitcnt vmcnt(6)" ::: "memory"); else asm volatile("s_waitcnt vmcnt(5)" ::: "memory");
;         __builtin_amdgcn_s_barrier();
;         { const int s2 = (cur >= 1) ? cur - 1 : 2; GEMM_ISSUE(s2, t + 2); }
;         compute(cur);
;         cur = (cur == 2) ? 0 : cur + 1;
;     }
	s_waitcnt lgkmcnt(0)
	v_mfma_f32_32x32x16_bf16 v[0:15], v[106:109], v[98:101], v[0:15]
	v_mfma_f32_32x32x16_bf16 v[48:63], v[102:105], v[88:91], v[48:63]
	v_mfma_f32_32x32x16_bf16 v[16:31], v[102:105], v[98:101], v[16:31]
	v_mfma_f32_32x32x16_bf16 v[32:47], v[106:109], v[88:91], v[32:47]
	v_lshl_add_u64 v[88:89], v[74:75], 0, s[36:37]
	global_load_lds_dwordx4 v[88:89], off
	v_lshl_add_u64 v[88:89], v[74:75], 0, s[50:51]
	s_mov_b32 m0, s9
	s_nop 0
	global_load_lds_dwordx4 v[88:89], off
	v_mfma_f32_32x32x16_bf16 v[0:15], v[122:125], v[114:117], v[0:15]
	v_lshl_add_u64 v[88:89], v[74:75], 0, s[52:53]
	s_mov_b64 s[52:53], 0x60680
	s_mov_b32 m0, s8
	s_mov_b64 s[8:9], 0x60000
	global_load_lds_dwordx4 v[88:89], off
	v_lshl_add_u64 v[88:89], v[74:75], 0, s[52:53]
	s_mov_b32 m0, s7
	v_mfma_f32_32x32x16_bf16 v[48:63], v[118:121], v[110:113], v[48:63]
	global_load_lds_dwordx4 v[88:89], off
	v_lshl_add_u64 v[88:89], v[76:77], 0, s[36:37]
	s_mov_b32 m0, s6
	s_mov_b64 s[6:7], 0x700
	global_load_lds_dwordx4 v[88:89], off
	v_lshl_add_u64 v[88:89], v[76:77], 0, s[50:51]
	s_mov_b32 m0, s5
	v_mfma_f32_32x32x16_bf16 v[16:31], v[118:121], v[114:117], v[16:31]
	global_load_lds_dwordx4 v[88:89], off
	s_mov_b32 m0, s15
	s_mov_b64 s[36:37], 0x40700
	v_mfma_f32_32x32x16_bf16 v[32:47], v[122:125], v[110:113], v[32:47]
	ds_read_b128 v[88:91], v68
	ds_read_b128 v[98:101], v68 offset:4096
	ds_read_b128 v[102:105], v69
	ds_read_b128 v[106:109], v69 offset:4096
	ds_read_b128 v[110:113], v70
	ds_read_b128 v[114:117], v70 offset:4096
	ds_read_b128 v[118:121], v71
	ds_read_b128 v[122:125], v71 offset:4096
	s_waitcnt lgkmcnt(0)
	v_mfma_f32_32x32x16_bf16 v[0:15], v[106:109], v[98:101], v[0:15]
	v_mfma_f32_32x32x16_bf16 v[48:63], v[102:105], v[88:91], v[48:63]
	v_mfma_f32_32x32x16_bf16 v[16:31], v[102:105], v[98:101], v[16:31]
	v_mfma_f32_32x32x16_bf16 v[32:47], v[106:109], v[88:91], v[32:47]
	ds_read_b128 v[88:91], v72
	ds_read_b128 v[98:101], v72 offset:4096
	ds_read_b128 v[102:105], v73
	ds_read_b128 v[106:109], v73 offset:4096
	v_mfma_f32_32x32x16_bf16 v[0:15], v[122:125], v[114:117], v[0:15]
	v_mfma_f32_32x32x16_bf16 v[48:63], v[118:121], v[110:113], v[48:63]
	v_mfma_f32_32x32x16_bf16 v[16:31], v[118:121], v[114:117], v[16:31]
	v_mfma_f32_32x32x16_bf16 v[32:47], v[122:125], v[110:113], v[32:47]
	ds_read_b128 v[110:113], v95
	ds_read_b128 v[114:117], v95 offset:4096
	ds_read_b128 v[118:121], v96
	ds_read_b128 v[122:125], v96 offset:4096
	s_waitcnt vmcnt(6)
	s_barrier
	s_waitcnt lgkmcnt(0)
	v_mfma_f32_32x32x16_bf16 v[0:15], v[106:109], v[98:101], v[0:15]
	v_mfma_f32_32x32x16_bf16 v[48:63], v[102:105], v[88:91], v[48:63]
	v_mfma_f32_32x32x16_bf16 v[16:31], v[102:105], v[98:101], v[16:31]
	v_mfma_f32_32x32x16_bf16 v[32:47], v[106:109], v[88:91], v[32:47]
	v_lshl_add_u64 v[88:89], v[74:75], 0, s[6:7]
	global_load_lds_dwordx4 v[88:89], off
	v_lshl_add_u64 v[88:89], v[74:75], 0, s[54:55]
	s_mov_b32 m0, s11
	s_mov_b64 s[10:11], 0x40000
	global_load_lds_dwordx4 v[88:89], off
	v_mfma_f32_32x32x16_bf16 v[0:15], v[122:125], v[114:117], v[0:15]
	v_lshl_add_u64 v[88:89], v[74:75], 0, s[36:37]
	s_mov_b64 s[36:37], 0x60700
	s_mov_b32 m0, s12
	s_nop 0
	global_load_lds_dwordx4 v[88:89], off
	v_lshl_add_u64 v[88:89], v[74:75], 0, s[36:37]
	s_mov_b32 m0, s13
	v_mfma_f32_32x32x16_bf16 v[48:63], v[118:121], v[110:113], v[48:63]
	global_load_lds_dwordx4 v[88:89], off
	v_lshl_add_u64 v[88:89], v[76:77], 0, s[6:7]
	s_mov_b32 m0, s14
	s_mov_b64 s[6:7], 0x40780
	global_load_lds_dwordx4 v[88:89], off
	v_lshl_add_u64 v[88:89], v[76:77], 0, s[54:55]
	s_mov_b32 m0, s20
	v_mfma_f32_32x32x16_bf16 v[16:31], v[118:121], v[114:117], v[16:31]
	global_load_lds_dwordx4 v[88:89], off
	s_mov_b32 m0, s21
	s_mov_b64 s[20:21], 0x60080
	v_mfma_f32_32x32x16_bf16 v[32:47], v[122:125], v[110:113], v[32:47]
	ds_read_b128 v[88:91], v80
	ds_read_b128 v[98:101], v80 offset:4096
	ds_read_b128 v[102:105], v64 offset:32768
	ds_read_b128 v[106:109], v64 offset:36864
	ds_read_b128 v[110:113], v81
	ds_read_b128 v[114:117], v81 offset:4096
	ds_read_b128 v[118:121], v82 offset:32768
	ds_read_b128 v[122:125], v82 offset:36864
	s_waitcnt lgkmcnt(0)
	v_mfma_f32_32x32x16_bf16 v[0:15], v[106:109], v[98:101], v[0:15]
	v_mfma_f32_32x32x16_bf16 v[48:63], v[102:105], v[88:91], v[48:63]
	v_mfma_f32_32x32x16_bf16 v[16:31], v[102:105], v[98:101], v[16:31]
	v_mfma_f32_32x32x16_bf16 v[32:47], v[106:109], v[88:91], v[32:47]
	ds_read_b128 v[88:91], v83
	ds_read_b128 v[98:101], v83 offset:4096
	ds_read_b128 v[102:105], v84 offset:32768
	ds_read_b128 v[106:109], v84 offset:36864
	v_mfma_f32_32x32x16_bf16 v[0:15], v[122:125], v[114:117], v[0:15]
	v_mfma_f32_32x32x16_bf16 v[48:63], v[118:121], v[110:113], v[48:63]
	v_mfma_f32_32x32x16_bf16 v[16:31], v[118:121], v[114:117], v[16:31]
	v_mfma_f32_32x32x16_bf16 v[32:47], v[122:125], v[110:113], v[32:47]
	ds_read_b128 v[110:113], v85
	ds_read_b128 v[114:117], v85 offset:4096
	ds_read_b128 v[118:121], v86 offset:32768
	ds_read_b128 v[122:125], v86 offset:36864
	s_waitcnt vmcnt(6)
	s_barrier
; template <int NI>
; DEVINL void gemm_kloop(const bf16_t* __restrict__ A, int lda, const bf16_t* __restrict__ Bt, int ldb, int K, int m0, int n0,
;                        unsigned char* lds, f32x16 (&acc)[NI][2]) {
;     ...
;     if (nt >= 2) {
;         if (NI == 2) asm volatile("s_waitcnt vmcnt(6)" ::: "memory"); else asm volatile("s_waitcnt vmcnt(5)" ::: "memory");
;         __builtin_amdgcn_s_barrier();
;         compute(cur);
;         cur = (cur == 2) ? 0 : cur + 1;
;     }
;     asm volatile("s_waitcnt vmcnt(0)" ::: "memory");
;     __builtin_amdgcn_s_barrier();
;     compute(cur);
	s_waitcnt lgkmcnt(0)
	v_mfma_f32_32x32x16_bf16 v[0:15], v[106:109], v[98:101], v[0:15]
	v_mfma_f32_32x32x16_bf16 v[48:63], v[102:105], v[88:91], v[48:63]
	v_mfma_f32_32x32x16_bf16 v[16:31], v[102:105], v[98:101], v[16:31]
	v_mfma_f32_32x32x16_bf16 v[32:47], v[106:109], v[88:91], v[32:47]
	v_lshl_add_u64 v[88:89], v[74:75], 0, vcc
	global_load_lds_dwordx4 v[88:89], off
	v_lshl_add_u64 v[88:89], v[74:75], 0, s[94:95]
	s_mov_b32 m0, s16
	s_nop 0
	global_load_lds_dwordx4 v[88:89], off
	v_mfma_f32_32x32x16_bf16 v[0:15], v[122:125], v[114:117], v[0:15]
	v_lshl_add_u64 v[88:89], v[74:75], 0, s[6:7]
	s_mov_b64 s[6:7], 0x60780
	s_mov_b32 m0, s17
	v_lshl_add_u64 v[74:75], v[74:75], 0, s[6:7]
	global_load_lds_dwordx4 v[88:89], off
	s_mov_b32 m0, s18
	v_mfma_f32_32x32x16_bf16 v[48:63], v[118:121], v[110:113], v[48:63]
	global_load_lds_dwordx4 v[74:75], off
	v_lshl_add_u64 v[74:75], v[76:77], 0, vcc
	s_mov_b32 m0, s19
	s_mov_b64 s[18:19], 0x40080
	global_load_lds_dwordx4 v[74:75], off
	v_lshl_add_u64 v[74:75], v[76:77], 0, s[94:95]
	s_mov_b32 m0, s24
	v_mfma_f32_32x32x16_bf16 v[16:31], v[118:121], v[114:117], v[16:31]
	global_load_lds_dwordx4 v[74:75], off
	s_mov_b64 s[24:25], 0x20100
	v_mfma_f32_32x32x16_bf16 v[32:47], v[122:125], v[110:113], v[32:47]
	ds_read_b128 v[74:77], v80 offset:49152
	ds_read_b128 v[88:91], v80 offset:53248
	ds_read_b128 v[98:101], v93
	ds_read_b128 v[102:105], v93 offset:4096
	ds_read_b128 v[106:109], v81 offset:49152
	ds_read_b128 v[110:113], v81 offset:53248
	ds_read_b128 v[114:117], v94
	ds_read_b128 v[118:121], v94 offset:4096
	s_waitcnt lgkmcnt(0)
	v_mfma_f32_32x32x16_bf16 v[0:15], v[102:105], v[88:91], v[0:15]
	v_mfma_f32_32x32x16_bf16 v[48:63], v[98:101], v[74:77], v[48:63]
	v_mfma_f32_32x32x16_bf16 v[16:31], v[98:101], v[88:91], v[16:31]
	v_mfma_f32_32x32x16_bf16 v[32:47], v[102:105], v[74:77], v[32:47]
	ds_read_b128 v[74:77], v83 offset:49152
	ds_read_b128 v[88:91], v83 offset:53248
	ds_read_b128 v[98:101], v66
	ds_read_b128 v[102:105], v66 offset:4096
	v_mfma_f32_32x32x16_bf16 v[0:15], v[118:121], v[110:113], v[0:15]
	v_mfma_f32_32x32x16_bf16 v[48:63], v[114:117], v[106:109], v[48:63]
	v_mfma_f32_32x32x16_bf16 v[16:31], v[114:117], v[110:113], v[16:31]
	v_mfma_f32_32x32x16_bf16 v[32:47], v[118:121], v[106:109], v[32:47]
	ds_read_b128 v[106:109], v85 offset:49152
	ds_read_b128 v[110:113], v85 offset:53248
	ds_read_b128 v[114:117], v67
	ds_read_b128 v[118:121], v67 offset:4096
	s_waitcnt vmcnt(6)
	s_barrier
	s_waitcnt lgkmcnt(0)
	v_mfma_f32_32x32x16_bf16 v[0:15], v[102:105], v[88:91], v[0:15]
	v_mfma_f32_32x32x16_bf16 v[48:63], v[98:101], v[74:77], v[48:63]
	v_mfma_f32_32x32x16_bf16 v[16:31], v[98:101], v[88:91], v[16:31]
	v_mfma_f32_32x32x16_bf16 v[32:47], v[102:105], v[74:77], v[32:47]
	v_mfma_f32_32x32x16_bf16 v[0:15], v[118:121], v[110:113], v[0:15]
	v_mfma_f32_32x32x16_bf16 v[48:63], v[114:117], v[106:109], v[48:63]
	v_mfma_f32_32x32x16_bf16 v[16:31], v[114:117], v[110:113], v[16:31]
	v_mfma_f32_32x32x16_bf16 v[32:47], v[118:121], v[106:109], v[32:47]
	ds_read_b128 v[74:77], v68
	ds_read_b128 v[88:91], v68 offset:4096
	ds_read_b128 v[98:101], v69
	ds_read_b128 v[66:69], v69 offset:4096
	ds_read_b128 v[102:105], v70
	ds_read_b128 v[106:109], v70 offset:4096
	ds_read_b128 v[110:113], v71
	ds_read_b128 v[114:117], v71 offset:4096
	s_waitcnt lgkmcnt(0)
	v_mfma_f32_32x32x16_bf16 v[0:15], v[66:69], v[88:91], v[0:15]
	v_mfma_f32_32x32x16_bf16 v[48:63], v[98:101], v[74:77], v[48:63]
	v_mfma_f32_32x32x16_bf16 v[16:31], v[98:101], v[88:91], v[16:31]
	v_mfma_f32_32x32x16_bf16 v[32:47], v[66:69], v[74:77], v[32:47]
	ds_read_b128 v[66:69], v72
	ds_read_b128 v[74:77], v72 offset:4096
	ds_read_b128 v[88:91], v73
	ds_read_b128 v[70:73], v73 offset:4096
	v_mfma_f32_32x32x16_bf16 v[0:15], v[114:117], v[106:109], v[0:15]
	v_mfma_f32_32x32x16_bf16 v[48:63], v[110:113], v[102:105], v[48:63]
	v_mfma_f32_32x32x16_bf16 v[16:31], v[110:113], v[106:109], v[16:31]
	v_mfma_f32_32x32x16_bf16 v[32:47], v[114:117], v[102:105], v[32:47]
	ds_read_b128 v[98:101], v95
	ds_read_b128 v[92:95], v95 offset:4096
	ds_read_b128 v[102:105], v96
	ds_read_b128 v[106:109], v96 offset:4096
	s_waitcnt vmcnt(0)
	s_barrier
	s_waitcnt lgkmcnt(0)
	v_mfma_f32_32x32x16_bf16 v[0:15], v[70:73], v[74:77], v[0:15]
	v_mfma_f32_32x32x16_bf16 v[48:63], v[88:91], v[66:69], v[48:63]
	v_mfma_f32_32x32x16_bf16 v[16:31], v[88:91], v[74:77], v[16:31]
	v_mfma_f32_32x32x16_bf16 v[32:47], v[70:73], v[66:69], v[32:47]
	v_mfma_f32_32x32x16_bf16 v[0:15], v[106:109], v[92:95], v[0:15]
	v_mfma_f32_32x32x16_bf16 v[48:63], v[102:105], v[98:101], v[48:63]
	v_mfma_f32_32x32x16_bf16 v[16:31], v[102:105], v[92:95], v[16:31]
	v_mfma_f32_32x32x16_bf16 v[32:47], v[106:109], v[98:101], v[32:47]
	ds_read_b128 v[66:69], v80
	ds_read_b128 v[70:73], v80 offset:4096
	ds_read_b128 v[74:77], v64 offset:32768
	ds_read_b128 v[88:91], v64 offset:36864
	ds_read_b128 v[92:95], v81
	ds_read_b128 v[96:99], v81 offset:4096
	ds_read_b128 v[100:103], v82 offset:32768
	ds_read_b128 v[104:107], v82 offset:36864
	s_waitcnt lgkmcnt(0)
	v_mfma_f32_32x32x16_bf16 v[0:15], v[88:91], v[70:73], v[0:15]
	v_mfma_f32_32x32x16_bf16 v[48:63], v[74:77], v[66:69], v[48:63]
	v_mfma_f32_32x32x16_bf16 v[32:47], v[88:91], v[66:69], v[32:47]
	v_mfma_f32_32x32x16_bf16 v[16:31], v[74:77], v[70:73], v[16:31]
	ds_read_b128 v[66:69], v83
	ds_read_b128 v[70:73], v83 offset:4096
	ds_read_b128 v[74:77], v84 offset:32768
	ds_read_b128 v[80:83], v84 offset:36864
	v_mfma_f32_32x32x16_bf16 v[0:15], v[104:107], v[96:99], v[0:15]
	v_mfma_f32_32x32x16_bf16 v[48:63], v[100:103], v[92:95], v[48:63]
	v_mfma_f32_32x32x16_bf16 v[32:47], v[104:107], v[92:95], v[32:47]
	v_mfma_f32_32x32x16_bf16 v[16:31], v[100:103], v[96:99], v[16:31]
	ds_read_b128 v[88:91], v85
	ds_read_b128 v[92:95], v85 offset:4096
	ds_read_b128 v[96:99], v86 offset:32768
	ds_read_b128 v[84:87], v86 offset:36864
	s_waitcnt lgkmcnt(0)
;     DEVINL bf16_t* U() const { return (bf16_t*)(ws + OFF_Z); }
; #define TID (opq_v((int)threadIdx.x))
; DEVINL unsigned cvt_pk_bf16(float lo, float hi) { const f32x2 v = {lo, hi}; return __builtin_bit_cast(unsigned, __builtin_convertvector(v, bf16x2v)); }
; DEVINL void store_rows_via_lds(unsigned char* lds, const u32x2 (&pk)[2][2][4], bf16_t* out_row0, int ld) {
;     const int tid = TID, lane = tid & 63, w = tid >> 6, r = lane & 31, h = lane >> 5;
;     unsigned char* reg = lds + w * (64 * 144);
;     __syncthreads();
; DEVINL void phase_up(const Ctx& c, unsigned char* lds) {
;     ...
;         const int mbase = tm * 256 + wm * 64, nbase = tn * 128 + wn * 64;
;         {
;             u32x2 pku[2][2][4];
; #pragma unroll
;             for (int mi = 0; mi < 2; ++mi)
; #pragma unroll
;                 for (int ni = 0; ni < 2; ++ni)
; #pragma unroll
;                     for (int g = 0; g < 4; ++g) {
;                         float v[4];
; #pragma unroll
;                         for (int j = 0; j < 4; ++j) { const float a = fmaxf(acc[ni][mi][4 * g + j], 0.f); v[j] = a * a; }
;                         pku[mi][ni][g][0] = cvt_pk_bf16(v[0], v[1]); pku[mi][ni][g][1] = cvt_pk_bf16(v[2], v[3]);
;                     }
;             store_rows_via_lds(lds, pku, c.U() + (size_t)mbase * DFF + nbase, DFF);
	v_mfma_f32_32x32x16_bf16 v[0:15], v[80:83], v[70:73], v[0:15]
	v_mfma_f32_32x32x16_bf16 v[48:63], v[74:77], v[66:69], v[48:63]
	v_mfma_f32_32x32x16_bf16 v[32:47], v[80:83], v[66:69], v[32:47]
	v_or_b32_e32 v66, s4, v78
	v_ashrrev_i32_e32 v67, 31, v66
	v_mfma_f32_32x32x16_bf16 v[16:31], v[74:77], v[70:73], v[16:31]
	v_mfma_f32_32x32x16_bf16 v[0:15], v[84:87], v[92:95], v[0:15]
	v_mfma_f32_32x32x16_bf16 v[48:63], v[96:99], v[88:91], v[48:63]
	s_nop 10
	v_max_f32_e32 v0, v0, v0
	v_max_f32_e32 v1, v1, v1
	v_max_f32_e32 v2, v2, v2
	v_max_f32_e32 v3, v3, v3
	v_max_f32_e32 v0, 0, v0
	v_max_f32_e32 v1, 0, v1
	v_max_f32_e32 v2, 0, v2
	v_mfma_f32_32x32x16_bf16 v[32:47], v[84:87], v[88:91], v[32:47]
	v_max_f32_e32 v3, 0, v3
	v_mul_f32_e64 v0, v0, v0
	v_mul_f32_e64 v1, v1, v1
	v_mul_f32_e64 v2, v2, v2
	v_mul_f32_e64 v3, v3, v3
	v_cvt_pk_bf16_f32 v0, v0, v1
	v_cvt_pk_bf16_f32 v1, v2, v3
	v_max_f32_e32 v2, v4, v4
	v_max_f32_e32 v3, v5, v5
	v_mfma_f32_32x32x16_bf16 v[16:31], v[96:99], v[92:95], v[16:31]
	v_max_f32_e32 v4, v6, v6
	v_max_f32_e32 v5, v7, v7
	v_max_f32_e32 v2, 0, v2
	v_max_f32_e32 v3, 0, v3
	v_max_f32_e32 v4, 0, v4
	v_max_f32_e32 v5, 0, v5
	v_pk_mul_f32 v[2:3], v[2:3], v[2:3]
	v_pk_mul_f32 v[4:5], v[4:5], v[4:5]
	v_cvt_pk_bf16_f32 v2, v2, v3
	v_cvt_pk_bf16_f32 v3, v4, v5
	v_max_f32_e32 v4, v8, v8
	v_max_f32_e32 v5, v9, v9
	v_max_f32_e32 v6, v10, v10
	v_max_f32_e32 v7, v11, v11
	v_max_f32_e32 v48, v48, v48
	v_max_f32_e32 v49, v49, v49
	v_max_f32_e32 v50, v50, v50
	v_max_f32_e32 v51, v51, v51
	v_max_f32_e32 v32, v32, v32
	v_max_f32_e32 v33, v33, v33
	v_max_f32_e32 v34, v34, v34
	v_max_f32_e32 v35, v35, v35
	v_max_f32_e32 v4, 0, v4
	v_max_f32_e32 v5, 0, v5
	v_max_f32_e32 v6, 0, v6
	v_max_f32_e32 v7, 0, v7
	v_max_f32_e32 v48, 0, v48
	v_max_f32_e32 v49, 0, v49
	v_max_f32_e32 v50, 0, v50
	v_max_f32_e32 v51, 0, v51
	v_max_f32_e32 v32, 0, v32
	v_max_f32_e32 v33, 0, v33
	v_max_f32_e32 v34, 0, v34
	v_max_f32_e32 v35, 0, v35
	v_max_f32_e32 v16, v16, v16
	v_max_f32_e32 v17, v17, v17
	v_max_f32_e32 v18, v18, v18
	v_max_f32_e32 v19, v19, v19
	v_pk_mul_f32 v[4:5], v[4:5], v[4:5]
	v_pk_mul_f32 v[6:7], v[6:7], v[6:7]
	v_pk_mul_f32 v[48:49], v[48:49], v[48:49]
	v_pk_mul_f32 v[50:51], v[50:51], v[50:51]
	v_pk_mul_f32 v[32:33], v[32:33], v[32:33]
	v_pk_mul_f32 v[34:35], v[34:35], v[34:35]
	v_max_f32_e32 v16, 0, v16
	v_max_f32_e32 v17, 0, v17
	v_max_f32_e32 v18, 0, v18
	v_max_f32_e32 v19, 0, v19
	v_cvt_pk_bf16_f32 v4, v4, v5
	v_cvt_pk_bf16_f32 v5, v6, v7
	v_max_f32_e32 v6, v12, v12
	v_max_f32_e32 v7, v13, v13
	v_max_f32_e32 v8, v14, v14
	v_max_f32_e32 v9, v15, v15
	v_cvt_pk_bf16_f32 v48, v48, v49
	v_cvt_pk_bf16_f32 v49, v50, v51
	v_max_f32_e32 v50, v52, v52
	v_max_f32_e32 v51, v53, v53
	v_max_f32_e32 v52, v54, v54
	v_max_f32_e32 v53, v55, v55
	v_cvt_pk_bf16_f32 v32, v32, v33
	v_cvt_pk_bf16_f32 v33, v34, v35
	v_max_f32_e32 v34, v36, v36
	v_max_f32_e32 v35, v37, v37
	v_max_f32_e32 v36, v38, v38
	v_max_f32_e32 v37, v39, v39
	v_pk_mul_f32 v[16:17], v[16:17], v[16:17]
	v_pk_mul_f32 v[18:19], v[18:19], v[18:19]
	v_max_f32_e32 v6, 0, v6
	v_max_f32_e32 v7, 0, v7
	v_max_f32_e32 v8, 0, v8
	v_max_f32_e32 v9, 0, v9
	v_max_f32_e32 v50, 0, v50
	v_max_f32_e32 v51, 0, v51
	v_max_f32_e32 v52, 0, v52
	v_max_f32_e32 v53, 0, v53
	v_max_f32_e32 v34, 0, v34
	v_max_f32_e32 v35, 0, v35
	v_max_f32_e32 v36, 0, v36
	v_max_f32_e32 v37, 0, v37
	v_cvt_pk_bf16_f32 v16, v16, v17
	v_cvt_pk_bf16_f32 v17, v18, v19
	v_max_f32_e32 v18, v20, v20
	v_max_f32_e32 v19, v21, v21
	v_max_f32_e32 v20, v22, v22
	v_max_f32_e32 v21, v23, v23
	v_pk_mul_f32 v[6:7], v[6:7], v[6:7]
	v_pk_mul_f32 v[8:9], v[8:9], v[8:9]
	v_pk_mul_f32 v[50:51], v[50:51], v[50:51]
	v_pk_mul_f32 v[52:53], v[52:53], v[52:53]
	v_pk_mul_f32 v[34:35], v[34:35], v[34:35]
	v_pk_mul_f32 v[36:37], v[36:37], v[36:37]
	v_max_f32_e32 v18, 0, v18
	v_max_f32_e32 v19, 0, v19
	v_max_f32_e32 v20, 0, v20
	v_max_f32_e32 v21, 0, v21
	v_cvt_pk_bf16_f32 v6, v6, v7
	v_cvt_pk_bf16_f32 v7, v8, v9
	v_add_u32_e32 v8, s1, v79
	v_lshlrev_b64 v[10:11], 13, v[66:67]
	v_cvt_pk_bf16_f32 v50, v50, v51
	v_cvt_pk_bf16_f32 v51, v52, v53
	v_max_f32_e32 v52, v56, v56
	v_max_f32_e32 v53, v57, v57
	v_max_f32_e32 v54, v58, v58
	v_max_f32_e32 v55, v59, v59
	v_cvt_pk_bf16_f32 v34, v34, v35
	v_cvt_pk_bf16_f32 v35, v36, v37
	v_max_f32_e32 v36, v40, v40
	v_max_f32_e32 v37, v41, v41
	v_max_f32_e32 v38, v42, v42
	v_max_f32_e32 v39, v43, v43
	v_pk_mul_f32 v[18:19], v[18:19], v[18:19]
	v_pk_mul_f32 v[20:21], v[20:21], v[20:21]
	v_lshl_add_u64 v[10:11], s[28:29], 0, v[10:11]
	v_ashrrev_i32_e32 v9, 31, v8
	v_max_f32_e32 v52, 0, v52
	v_max_f32_e32 v53, 0, v53
	v_max_f32_e32 v54, 0, v54
	v_max_f32_e32 v55, 0, v55
	v_max_f32_e32 v36, 0, v36
	v_max_f32_e32 v37, 0, v37
	v_max_f32_e32 v38, 0, v38
	v_max_f32_e32 v39, 0, v39
	v_cvt_pk_bf16_f32 v18, v18, v19
	v_cvt_pk_bf16_f32 v19, v20, v21
	v_max_f32_e32 v20, v24, v24
	v_max_f32_e32 v21, v25, v25
	v_max_f32_e32 v22, v26, v26
	v_max_f32_e32 v23, v27, v27
	v_lshl_add_u64 v[8:9], v[8:9], 1, v[10:11]
	v_mov_b32_e32 v10, v160
	v_pk_mul_f32 v[52:53], v[52:53], v[52:53]
	v_pk_mul_f32 v[54:55], v[54:55], v[54:55]
	v_pk_mul_f32 v[36:37], v[36:37], v[36:37]
	v_pk_mul_f32 v[38:39], v[38:39], v[38:39]
	v_max_f32_e32 v20, 0, v20
	v_max_f32_e32 v21, 0, v21
	v_max_f32_e32 v22, 0, v22
	v_max_f32_e32 v23, 0, v23
	v_cvt_pk_bf16_f32 v52, v52, v53
	v_lshrrev_b32_e32 v11, 6, v10
	v_cvt_pk_bf16_f32 v53, v54, v55
	v_max_f32_e32 v54, v60, v60
	v_max_f32_e32 v55, v61, v61
	v_max_f32_e32 v56, v62, v62
	v_max_f32_e32 v57, v63, v63
	v_cvt_pk_bf16_f32 v36, v36, v37
	v_cvt_pk_bf16_f32 v37, v38, v39
	v_max_f32_e32 v38, v44, v44
	v_max_f32_e32 v39, v45, v45
	v_max_f32_e32 v40, v46, v46
	v_max_f32_e32 v41, v47, v47
	v_pk_mul_f32 v[20:21], v[20:21], v[20:21]
	v_pk_mul_f32 v[22:23], v[22:23], v[22:23]
	v_and_b32_e32 v12, 31, v10
	v_mul_lo_u32 v11, v11, s38
	v_lshrrev_b32_e32 v13, 2, v10
	v_max_f32_e32 v54, 0, v54
	v_max_f32_e32 v55, 0, v55
	v_max_f32_e32 v56, 0, v56
	v_max_f32_e32 v57, 0, v57
	v_max_f32_e32 v38, 0, v38
	v_max_f32_e32 v39, 0, v39
	v_max_f32_e32 v40, 0, v40
	v_max_f32_e32 v41, 0, v41
	v_cvt_pk_bf16_f32 v20, v20, v21
	v_cvt_pk_bf16_f32 v21, v22, v23
	v_max_f32_e32 v22, v28, v28
	v_max_f32_e32 v23, v29, v29
	v_max_f32_e32 v24, v30, v30
	v_max_f32_e32 v25, v31, v31
	v_add_u32_e32 v11, 0xc000, v11
	v_mul_u32_u24_e32 v12, 0x90, v12
	v_and_b32_e32 v13, 8, v13
	v_pk_mul_f32 v[54:55], v[54:55], v[54:55]
	v_pk_mul_f32 v[56:57], v[56:57], v[56:57]
	v_pk_mul_f32 v[38:39], v[38:39], v[38:39]
	v_pk_mul_f32 v[40:41], v[40:41], v[40:41]
	v_max_f32_e32 v22, 0, v22
	v_max_f32_e32 v23, 0, v23
	v_max_f32_e32 v24, 0, v24
	v_max_f32_e32 v25, 0, v25
	v_add3_u32 v12, v11, v12, v13
	v_cvt_pk_bf16_f32 v54, v54, v55
	v_cvt_pk_bf16_f32 v55, v56, v57
	v_cvt_pk_bf16_f32 v38, v38, v39
	v_cvt_pk_bf16_f32 v39, v40, v41
	v_pk_mul_f32 v[22:23], v[22:23], v[22:23]
	v_pk_mul_f32 v[24:25], v[24:25], v[24:25]
	s_waitcnt vmcnt(0)
; DEVINL void store_rows_via_lds(unsigned char* lds, const u32x2 (&pk)[2][2][4], bf16_t* out_row0, int ld) {
;     ...
;     __syncthreads();
; #pragma unroll
;     for (int mi = 0; mi < 2; ++mi)
; #pragma unroll
;         for (int ni = 0; ni < 2; ++ni)
; #pragma unroll
;             for (int g = 0; g < 4; ++g) *(u32x2*)(reg + (mi * 32 + r) * 144 + (ni * 32 + 8 * g + 4 * h) * 2) = pk[mi][ni][g];
;     __syncthreads();
; #pragma unroll
;     for (int it = 0; it < 8; ++it) {
;         const int idx = it * 64 + lane, row = idx >> 3, c16 = idx & 7;
;         const u32x4 v = *(const u32x4*)(reg + row * 144 + c16 * 16);
;         *(u32x4*)(out_row0 + (size_t)row * ld + c16 * 8) = v;
;     }
	s_nop 0
	ds_write2_b64 v12, v[48:49], v[50:51] offset1:2
	ds_write2_b64 v12, v[52:53], v[54:55] offset0:4 offset1:6
	ds_write2_b64 v12, v[32:33], v[34:35] offset0:8 offset1:10
	ds_write2_b64 v12, v[36:37], v[38:39] offset0:12 offset1:14
	v_add_u32_e32 v12, 0x1000, v12
	v_cvt_pk_bf16_f32 v22, v22, v23
	v_cvt_pk_bf16_f32 v23, v24, v25
	ds_write2_b64 v12, v[16:17], v[18:19] offset0:64 offset1:66
	ds_write2_b64 v12, v[20:21], v[22:23] offset0:68 offset1:70
	ds_write2_b64 v12, v[0:1], v[2:3] offset0:72 offset1:74
	ds_write2_b64 v12, v[4:5], v[6:7] offset0:76 offset1:78
	v_lshlrev_b32_e32 v0, 4, v10
	v_bfe_u32 v6, v10, 3, 3
	v_and_b32_e32 v64, 0x70, v0
	v_mul_u32_u24_e32 v2, 0x90, v6
	v_lshl_add_u64 v[0:1], v[8:9], 0, v[64:65]
	v_add3_u32 v8, v11, v64, v2
	s_waitcnt lgkmcnt(0)
	s_nop 0
	ds_read_b128 v[2:5], v8
	v_lshlrev_b32_e32 v64, 13, v6
	v_lshl_add_u64 v[6:7], v[0:1], 0, v[64:65]
	s_waitcnt lgkmcnt(0)
	global_store_dwordx4 v[6:7], v[2:5], off
	ds_read_b128 v[2:5], v8 offset:1152
	v_or_b32_e32 v6, 0x10000, v64
	v_mov_b32_e32 v7, v65
	v_lshl_add_u64 v[6:7], v[0:1], 0, v[6:7]
	s_waitcnt lgkmcnt(0)
	global_store_dwordx4 v[6:7], v[2:5], off
	ds_read_b128 v[2:5], v8 offset:2304
	v_or_b32_e32 v6, 0x20000, v64
	v_mov_b32_e32 v7, v65
	v_lshl_add_u64 v[6:7], v[0:1], 0, v[6:7]
	s_waitcnt lgkmcnt(0)
	global_store_dwordx4 v[6:7], v[2:5], off
	ds_read_b128 v[2:5], v8 offset:3456
	v_or_b32_e32 v6, 0x30000, v64
	v_mov_b32_e32 v7, v65
	v_lshl_add_u64 v[6:7], v[0:1], 0, v[6:7]
	s_waitcnt lgkmcnt(0)
	global_store_dwordx4 v[6:7], v[2:5], off
	ds_read_b128 v[2:5], v8 offset:4608
	v_or_b32_e32 v6, 0x40000, v64
	v_mov_b32_e32 v7, v65
	v_lshl_add_u64 v[6:7], v[0:1], 0, v[6:7]
	s_waitcnt lgkmcnt(0)
	global_store_dwordx4 v[6:7], v[2:5], off
	ds_read_b128 v[2:5], v8 offset:5760
	v_or_b32_e32 v6, 0x50000, v64
	v_mov_b32_e32 v7, v65
	v_lshl_add_u64 v[6:7], v[0:1], 0, v[6:7]
	s_waitcnt lgkmcnt(0)
	global_store_dwordx4 v[6:7], v[2:5], off
	ds_read_b128 v[2:5], v8 offset:6912
	v_or_b32_e32 v6, 0x60000, v64
	v_mov_b32_e32 v7, v65
	v_lshl_add_u64 v[6:7], v[0:1], 0, v[6:7]
	v_or_b32_e32 v64, 0x70000, v64
	s_waitcnt lgkmcnt(0)
	global_store_dwordx4 v[6:7], v[2:5], off
	ds_read_b128 v[2:5], v8 offset:8064
	v_lshl_add_u64 v[0:1], v[0:1], 0, v[64:65]
	s_waitcnt lgkmcnt(0)
	global_store_dwordx4 v[0:1], v[2:5], off
	s_cbranch_scc0 .LBB0_45

;     DEVINL bf16_t* Z() const { return (bf16_t*)(ws + OFF_Z); }
; #define TID (opq_v((int)threadIdx.x))
; DEVINL unsigned cvt_pk_bf16(float lo, float hi) { const f32x2 v = {lo, hi}; return __builtin_bit_cast(unsigned, __builtin_convertvector(v, bf16x2v)); }
; DEVINL void store_rows_via_lds(unsigned char* lds, const u32x2 (&pk)[2][2][4], bf16_t* out_row0, int ld) {
;     const int tid = TID, lane = tid & 63, w = tid >> 6, r = lane & 31, h = lane >> 5;
;     unsigned char* reg = lds + w * (64 * 144);
;     __syncthreads();
; #pragma unroll
;     for (int mi = 0; mi < 2; ++mi)
; #pragma unroll
;         for (int ni = 0; ni < 2; ++ni)
; #pragma unroll
;             for (int g = 0; g < 4; ++g) *(u32x2*)(reg + (mi * 32 + r) * 144 + (ni * 32 + 8 * g + 4 * h) * 2) = pk[mi][ni][g];
;     __syncthreads();
; #pragma unroll
;     for (int it = 0; it < 8; ++it) {
;         const int idx = it * 64 + lane, row = idx >> 3, c16 = idx & 7;
;         const u32x4 v = *(const u32x4*)(reg + row * 144 + c16 * 16);
;         *(u32x4*)(out_row0 + (size_t)row * ld + c16 * 8) = v;
;     }
; DEVINL void epi_inproj(const Ctx& c, int layer, f32x16 (&acc)[2][2], int mbase, int nbase, unsigned char* lds) {
;     ...
;                 { u32x2 o; o[0] = cvt_pk_bf16(v[0], v[1]); o[1] = cvt_pk_bf16(v[2], v[3]); pkz[mi][ni][g] = o; }
;             }
;     }
;     if (zc >= 0) store_rows_via_lds(lds, pkz, c.Z() + (size_t)mbase * ZW + zc, ZW);
.LBB0_536:
	s_or_b64 exec, exec, s[6:7]
	v_cvt_pk_bf16_f32 v0, v24, v25
	v_cvt_pk_bf16_f32 v1, v26, v27
	v_cvt_pk_bf16_f32 v2, v20, v21
	v_cvt_pk_bf16_f32 v3, v22, v23
	v_cvt_pk_bf16_f32 v4, v16, v17
	v_cvt_pk_bf16_f32 v5, v18, v19
	v_cvt_pk_bf16_f32 v6, v46, v47
	v_cvt_pk_bf16_f32 v7, v90, v91
	v_cvt_pk_bf16_f32 v8, v42, v43
	v_cvt_pk_bf16_f32 v9, v44, v45
	v_cvt_pk_bf16_f32 v10, v38, v39
	v_cvt_pk_bf16_f32 v11, v40, v41
	v_cvt_pk_bf16_f32 v12, v32, v33
	v_cvt_pk_bf16_f32 v13, v34, v35
	v_cvt_pk_bf16_f32 v14, v60, v61
	v_cvt_pk_bf16_f32 v15, v62, v63
	v_cvt_pk_bf16_f32 v18, v56, v57
	v_cvt_pk_bf16_f32 v19, v58, v59
	v_cvt_pk_bf16_f32 v20, v52, v53
	v_cvt_pk_bf16_f32 v21, v54, v55
	v_cvt_pk_bf16_f32 v22, v48, v49
	v_cvt_pk_bf16_f32 v23, v50, v51
	v_cvt_pk_bf16_f32 v24, v86, v87
	v_cvt_pk_bf16_f32 v25, v88, v89
	v_cvt_pk_bf16_f32 v26, v82, v83
	v_cvt_pk_bf16_f32 v27, v84, v85
	v_cvt_pk_bf16_f32 v32, v78, v79
	v_cvt_pk_bf16_f32 v33, v80, v81
	v_cvt_pk_bf16_f32 v34, v74, v75
	v_cvt_pk_bf16_f32 v35, v76, v77
	v_or_b32_e32 v36, s36, v73
	v_cvt_pk_bf16_f32 v16, v28, v29
	v_cvt_pk_bf16_f32 v17, v30, v31
	v_cmp_lt_i32_e32 vcc, -1, v66
	s_and_saveexec_b64 s[6:7], vcc
	s_cbranch_execz .LBB0_538
	v_readlane_b32 s8, v247, 7
	v_readlane_b32 s9, v247, 8
	v_mov_b32_e32 v30, v160
	s_waitcnt vmcnt(0)
	v_mov_b64_e32 v[28:29], s[8:9]
	v_mad_i64_i32 v[28:29], s[8:9], v36, s49, v[28:29]
	v_lshrrev_b32_e32 v31, 6, v30
	s_movk_i32 s8, 0x2400
	v_and_b32_e32 v37, 31, v30
	v_mul_lo_u32 v31, v31, s8
	v_lshrrev_b32_e32 v38, 2, v30
	v_add_u32_e32 v31, 0xc000, v31
	v_mul_u32_u24_e32 v37, 0x90, v37
	v_and_b32_e32 v38, 8, v38
	v_add3_u32 v37, v31, v37, v38
	s_nop 0
	ds_write2_b64 v37, v[34:35], v[32:33] offset1:2
	ds_write2_b64 v37, v[26:27], v[24:25] offset0:4 offset1:6
	ds_write2_b64 v37, v[22:23], v[20:21] offset0:8 offset1:10
	ds_write2_b64 v37, v[18:19], v[14:15] offset0:12 offset1:14
	v_add_u32_e32 v37, 0x1000, v37
	v_mov_b32_e32 v67, v65
	ds_write2_b64 v37, v[12:13], v[10:11] offset0:64 offset1:66
	ds_write2_b64 v37, v[8:9], v[6:7] offset0:68 offset1:70
	ds_write2_b64 v37, v[4:5], v[2:3] offset0:72 offset1:74
	ds_write2_b64 v37, v[0:1], v[16:17] offset0:76 offset1:78
	v_lshlrev_b32_e32 v37, 4, v30
	v_lshl_add_u64 v[28:29], v[66:67], 1, v[28:29]
	v_and_b32_e32 v64, 0x70, v37
	v_bfe_u32 v37, v30, 3, 3
	v_lshl_add_u64 v[42:43], v[28:29], 0, v[64:65]
	v_mul_u32_u24_e32 v28, 0x90, v37
	v_add3_u32 v48, v31, v64, v28
	s_waitcnt lgkmcnt(0)
	s_nop 0
	ds_read_b128 v[28:31], v48
	ds_read_b128 v[38:41], v48 offset:1152
	v_mul_u32_u24_e32 v37, 0x2200, v37
	v_lshlrev_b32_e32 v64, 1, v37
	v_lshl_add_u64 v[44:45], v[42:43], 0, v[64:65]
	s_mov_b32 s8, 0x22000
	s_waitcnt lgkmcnt(1)
	global_store_dwordx4 v[44:45], v[28:31], off
	s_nop 1
	v_add_co_u32_e32 v28, vcc, s8, v44
	s_mov_b32 s8, 0x44000
	s_nop 0
	v_addc_co_u32_e32 v29, vcc, 0, v45, vcc
	s_waitcnt lgkmcnt(0)
	global_store_dwordx4 v[28:29], v[38:41], off
	ds_read_b128 v[28:31], v48 offset:2304
	ds_read_b128 v[38:41], v48 offset:3456
	v_add_co_u32_e32 v46, vcc, s8, v44
	s_mov_b32 s8, 0x66000
	s_nop 0
	v_addc_co_u32_e32 v47, vcc, 0, v45, vcc
	s_waitcnt lgkmcnt(1)
	global_store_dwordx4 v[46:47], v[28:31], off
	s_nop 1
	v_add_co_u32_e32 v28, vcc, s8, v44
	s_mov_b32 s8, 0x88000
	s_nop 0
	v_addc_co_u32_e32 v29, vcc, 0, v45, vcc
	s_waitcnt lgkmcnt(0)
	global_store_dwordx4 v[28:29], v[38:41], off
	ds_read_b128 v[28:31], v48 offset:4608
	ds_read_b128 v[38:41], v48 offset:5760
	v_add_co_u32_e32 v44, vcc, s8, v44
	s_nop 1
	v_addc_co_u32_e32 v45, vcc, 0, v45, vcc
	s_waitcnt lgkmcnt(1)
	global_store_dwordx4 v[44:45], v[28:31], off
	v_add_u32_e32 v44, 0xcc000, v64
	v_mov_b32_e32 v45, v65
	v_add_u32_e32 v28, 0xaa000, v64
	v_mov_b32_e32 v29, v65
	v_lshl_add_u64 v[28:29], v[42:43], 0, v[28:29]
	s_waitcnt lgkmcnt(0)
	global_store_dwordx4 v[28:29], v[38:41], off
	ds_read_b128 v[28:31], v48 offset:6912
	ds_read_b128 v[38:41], v48 offset:8064
	v_lshl_add_u64 v[44:45], v[42:43], 0, v[44:45]
	v_add_u32_e32 v64, 0xee000, v64
	s_waitcnt lgkmcnt(1)
	global_store_dwordx4 v[44:45], v[28:31], off
	s_nop 1
	v_lshl_add_u64 v[28:29], v[42:43], 0, v[64:65]
	s_waitcnt lgkmcnt(0)
	global_store_dwordx4 v[28:29], v[38:41], off
	s_or_b64 exec, exec, s[6:7]
	v_cmp_ne_u64_e32 vcc, 0, v[68:69]
	s_and_saveexec_b64 s[6:7], vcc
	s_cbranch_execz .LBB0_363
	s_branch .LBB0_539

; #define TID (opq_v((int)threadIdx.x))
; DEVINL void store_cols_via_lds(unsigned char* lds, const u32x2 (&pk)[2][2][4], bf16_t* vt_col0  ) {
;     const int tid = TID, lane = tid & 63, w = tid >> 6, r = lane & 31, h = lane >> 5;
;     unsigned char* reg = lds + w * (64 * 144);
;     __syncthreads();
; #pragma unroll
;     for (int mi = 0; mi < 2; ++mi)
; #pragma unroll
;         for (int ni = 0; ni < 2; ++ni)
; #pragma unroll
;             for (int g = 0; g < 4; ++g) {
;                 const int n = ni * 32 + 8 * g + 4 * h, m = mi * 32 + r;
;                 *(bf16_t*)(reg + (n + 0) * 144 + m * 2) = (bf16_t)(pk[mi][ni][g][0] & 0xffffu);
;                 *(bf16_t*)(reg + (n + 1) * 144 + m * 2) = (bf16_t)(pk[mi][ni][g][0] >> 16);
;                 *(bf16_t*)(reg + (n + 2) * 144 + m * 2) = (bf16_t)(pk[mi][ni][g][1] & 0xffffu);
;                 *(bf16_t*)(reg + (n + 3) * 144 + m * 2) = (bf16_t)(pk[mi][ni][g][1] >> 16);
;             }
;     __syncthreads();
; #pragma unroll
;     for (int it = 0; it < 8; ++it) {
;         const int idx = it * 64 + lane, n = idx >> 3, c16 = idx & 7;
;         const u32x4 v = *(const u32x4*)(reg + n * 144 + c16 * 16);
;         *(u32x4*)(vt_col0 + (size_t)n * L + c16 * 8) = v;
;     }
; }
; DEVINL void epi_inproj(const Ctx& c, int layer, f32x16 (&acc)[2][2], int mbase, int nbase, unsigned char* lds) {
;     ...
;     if (vt) { const int b0 = mbase / L, p0 = mbase - b0 * L; store_cols_via_lds(lds, pkz, vt + ((size_t)(b0 * vC + vcol)) * L + p0); }
.LBB0_539:
	s_mov_b32 s8, 0x78787879
	v_mul_hi_i32 v28, v36, s8
	v_lshrrev_b32_e32 v29, 31, v28
	v_ashrrev_i32_e32 v28, 10, v28
	v_add_u32_e32 v29, v28, v29
	s_movk_i32 s8, 0xf780
	v_mad_i32_i24 v28, v29, s8, v36
	v_mad_i32_i24 v29, v94, v29, v93
	s_movk_i32 s8, 0x1100
	v_mad_i64_i32 v[30:31], s[8:9], v29, s8, v[68:69]
	v_ashrrev_i32_e32 v29, 31, v28
	v_lshl_add_u64 v[28:29], v[28:29], 1, v[30:31]
	v_mov_b32_e32 v30, v160
	s_movk_i32 s8, 0x2400
	v_lshrrev_b32_e32 v31, 6, v30
	v_lshrrev_b32_e32 v36, 3, v30
	v_mul_lo_u32 v31, v31, s8
	v_and_b32_e32 v36, 4, v36
	v_lshlrev_b32_e32 v37, 1, v30
	v_add_u32_e32 v31, 0xc000, v31
	v_and_b32_e32 v37, 62, v37
	v_mul_u32_u24_e32 v36, 0x90, v36
	v_add3_u32 v36, v31, v36, v37
	s_waitcnt vmcnt(0)
	s_nop 0
	ds_write_b16 v36, v34
	ds_write_b16_d16_hi v36, v34 offset:144
	ds_write_b16 v36, v35 offset:288
	ds_write_b16_d16_hi v36, v35 offset:432
	ds_write_b16 v36, v32 offset:1152
	ds_write_b16_d16_hi v36, v32 offset:1296
	ds_write_b16 v36, v33 offset:1440
	ds_write_b16_d16_hi v36, v33 offset:1584
	ds_write_b16 v36, v26 offset:2304
	ds_write_b16_d16_hi v36, v26 offset:2448
	ds_write_b16 v36, v27 offset:2592
	ds_write_b16_d16_hi v36, v27 offset:2736
	ds_write_b16 v36, v24 offset:3456
	ds_write_b16_d16_hi v36, v24 offset:3600
	ds_write_b16 v36, v25 offset:3744
	ds_write_b16_d16_hi v36, v25 offset:3888
	ds_write_b16 v36, v22 offset:4608
	ds_write_b16_d16_hi v36, v22 offset:4752
	ds_write_b16 v36, v23 offset:4896
	ds_write_b16_d16_hi v36, v23 offset:5040
	ds_write_b16 v36, v20 offset:5760
	ds_write_b16_d16_hi v36, v20 offset:5904
	ds_write_b16 v36, v21 offset:6048
	ds_write_b16_d16_hi v36, v21 offset:6192
	ds_write_b16 v36, v18 offset:6912
	ds_write_b16_d16_hi v36, v18 offset:7056
	ds_write_b16 v36, v19 offset:7200
	ds_write_b16_d16_hi v36, v19 offset:7344
	ds_write_b16 v36, v14 offset:8064
	ds_write_b16_d16_hi v36, v14 offset:8208
	ds_write_b16 v36, v15 offset:8352
	ds_write_b16_d16_hi v36, v15 offset:8496
	ds_write_b16 v36, v12 offset:64
	ds_write_b16_d16_hi v36, v12 offset:208
	ds_write_b16 v36, v13 offset:352
	ds_write_b16_d16_hi v36, v13 offset:496
	ds_write_b16 v36, v10 offset:1216
	ds_write_b16_d16_hi v36, v10 offset:1360
	ds_write_b16 v36, v11 offset:1504
	ds_write_b16_d16_hi v36, v11 offset:1648
	ds_write_b16 v36, v8 offset:2368
	ds_write_b16_d16_hi v36, v8 offset:2512
	ds_write_b16 v36, v9 offset:2656
	ds_write_b16_d16_hi v36, v9 offset:2800
	ds_write_b16 v36, v6 offset:3520
	ds_write_b16_d16_hi v36, v6 offset:3664
	ds_write_b16 v36, v7 offset:3808
	ds_write_b16_d16_hi v36, v7 offset:3952
	ds_write_b16 v36, v4 offset:4672
	ds_write_b16_d16_hi v36, v4 offset:4816
	ds_write_b16 v36, v5 offset:4960
	ds_write_b16_d16_hi v36, v5 offset:5104
	ds_write_b16 v36, v2 offset:5824
	ds_write_b16_d16_hi v36, v2 offset:5968
	ds_write_b16 v36, v3 offset:6112
	ds_write_b16_d16_hi v36, v3 offset:6256
	ds_write_b16 v36, v0 offset:6976
	ds_write_b16_d16_hi v36, v0 offset:7120
	ds_write_b16 v36, v1 offset:7264
	ds_write_b16_d16_hi v36, v1 offset:7408
	ds_write_b16 v36, v16 offset:8128
	ds_write_b16_d16_hi v36, v16 offset:8272
	ds_write_b16 v36, v17 offset:8416
	ds_write_b16_d16_hi v36, v17 offset:8560
	v_lshlrev_b32_e32 v0, 4, v30
	v_bfe_u32 v4, v30, 3, 3
	v_and_b32_e32 v64, 0x70, v0
	v_mul_u32_u24_e32 v0, 0x90, v4
	v_add3_u32 v14, v31, v64, v0
	s_waitcnt lgkmcnt(0)
	s_nop 0
	ds_read_b128 v[0:3], v14
	v_mul_u32_u24_e32 v4, 0x880, v4
	v_lshl_add_u64 v[8:9], v[28:29], 0, v[64:65]
	v_lshlrev_b32_e32 v64, 1, v4
	ds_read_b128 v[4:7], v14 offset:1152
	v_lshl_add_u64 v[10:11], v[8:9], 0, v[64:65]
	s_mov_b32 s8, 0x8000
	s_waitcnt lgkmcnt(1)
	global_store_dwordx4 v[10:11], v[0:3], off
	s_nop 1
	v_add_co_u32_e32 v0, vcc, s8, v10
	s_mov_b32 s8, 0x11000
	s_nop 0
	v_addc_co_u32_e32 v1, vcc, 0, v11, vcc
	s_waitcnt lgkmcnt(0)
	global_store_dwordx4 v[0:1], v[4:7], off offset:2048
	ds_read_b128 v[0:3], v14 offset:2304
	ds_read_b128 v[4:7], v14 offset:3456
	v_add_co_u32_e32 v12, vcc, s8, v10
	s_mov_b32 s8, 0x19000
	s_nop 0
	v_addc_co_u32_e32 v13, vcc, 0, v11, vcc
	s_waitcnt lgkmcnt(1)
	global_store_dwordx4 v[12:13], v[0:3], off
	s_nop 1
	v_add_co_u32_e32 v0, vcc, s8, v10
	s_mov_b32 s8, 0x22000
	s_nop 0
	v_addc_co_u32_e32 v1, vcc, 0, v11, vcc
	s_waitcnt lgkmcnt(0)
	global_store_dwordx4 v[0:1], v[4:7], off offset:2048
	ds_read_b128 v[0:3], v14 offset:4608
	ds_read_b128 v[4:7], v14 offset:5760
	v_add_co_u32_e32 v10, vcc, s8, v10
	s_nop 1
	v_addc_co_u32_e32 v11, vcc, 0, v11, vcc
	s_waitcnt lgkmcnt(1)
	global_store_dwordx4 v[10:11], v[0:3], off
	v_add_u32_e32 v10, 0x33000, v64
	v_mov_b32_e32 v11, v65
	v_add_u32_e32 v0, 0x2a800, v64
	v_mov_b32_e32 v1, v65
	v_lshl_add_u64 v[0:1], v[8:9], 0, v[0:1]
	s_waitcnt lgkmcnt(0)
	global_store_dwordx4 v[0:1], v[4:7], off
	ds_read_b128 v[0:3], v14 offset:6912
	ds_read_b128 v[4:7], v14 offset:8064
	v_lshl_add_u64 v[10:11], v[8:9], 0, v[10:11]
	v_add_u32_e32 v64, 0x3b800, v64
	s_waitcnt lgkmcnt(1)
	global_store_dwordx4 v[10:11], v[0:3], off
	s_nop 1
	v_lshl_add_u64 v[0:1], v[8:9], 0, v[64:65]
	s_waitcnt lgkmcnt(0)
	global_store_dwordx4 v[0:1], v[4:7], off
	s_branch .LBB0_363
